# hand-written gated branch GEMM (skewed pipeline, prefetched gates) + outproj epilogue loads up front
# speedup vs baseline: 1.0265x; 1.0265x over previous
.LBB0_212:
	s_and_b64 vcc, exec, s[2:3]
	s_cbranch_vccz .LBB0_314
	v_readlane_b32 s76, v254, 6
	v_readlane_b32 s84, v254, 8
	v_readlane_b32 s90, v252, 4
	s_cmp_gt_i32 s92, 1
	s_mov_b32 s86, s76
	v_readlane_b32 s85, v254, 9
	v_readlane_b32 s91, v252, 5
	v_readlane_b32 s77, v254, 7
	s_cbranch_scc0 .LBB0_230
	s_cmp_gt_i32 s92, 2
	s_mov_b64 s[2:3], -1
	s_mov_b32 s24, 0x34000
	s_mov_b32 s25, 0x68000
	s_mov_b32 s30, 0x9c000
	s_cbranch_scc0 .LBB0_310
	s_waitcnt vmcnt(0) lgkmcnt(0)
	v_readlane_b32 s2, v253, 0
	v_readlane_b32 s3, v254, 4
	v_readlane_b32 s80, v254, 50
	v_readlane_b32 s81, v254, 51
	s_and_b32 s77, s2, 7
	s_lshl_b32 s77, s77, 2
	s_lshr_b32 s78, s2, 3
	s_lshr_b32 s79, s3, 3
	s_cmp_gt_u32 s78, 31
	s_cbranch_scc1 .LBB0_309
	v_and_b32_e32 v170, 15, v1
	v_bfe_u32 v171, v1, 4, 2
	v_bfe_u32 v172, v1, 6, 1
	v_lshrrev_b32_e32 v173, 7, v1
	v_and_b32_e32 v162, 7, v170
	v_xor_b32_e32 v162, v162, v171
	v_lshlrev_b32_e32 v162, 4, v162
	v_lshlrev_b32_e32 v200, 13, v173
	v_lshl_add_u32 v200, v170, 7, v200
	v_add_u32_e32 v200, v200, v162
	v_xor_b32_e32 v201, 64, v200
	v_lshlrev_b32_e32 v202, 13, v172
	v_lshl_add_u32 v202, v170, 7, v202
	v_add_u32_e32 v202, v202, v162
	v_add_u32_e32 v202, 0x8000, v202
	v_xor_b32_e32 v203, 64, v202
	v_lshl_add_u32 v162, v173, 6, v170
	v_lshlrev_b32_e32 v172, 7, v172
	v_lshl_add_u32 v172, v171, 3, v172
	v_mul_u32_u24_e32 v206, 0x3400, v162
	v_add_u32_e32 v206, v206, v172
	v_add_u32_e32 v207, 0x34000, v206
	v_add_u32_e32 v208, 0x68000, v206
	v_add_u32_e32 v209, 0x9c000, v206
	v_lshl_add_u32 v210, v162, 11, v172
	v_add_u32_e32 v211, 0x8000, v210
	v_add_u32_e32 v168, 0x10000, v210
	v_add_u32_e32 v169, 0x18000, v210
	v_lshrrev_b32_e32 v170, 3, v1
	v_and_b32_e32 v171, 7, v1
	v_and_b32_e32 v173, 7, v170
	v_xor_b32_e32 v171, v171, v173
	v_lshlrev_b32_e32 v171, 4, v171
	v_mul_u32_u24_e32 v196, 0xc00, v170
	v_add_u32_e32 v196, v196, v171
	v_add_u32_e32 v197, 0x30000, v196
	v_add_u32_e32 v198, 0x60000, v196
	v_add_u32_e32 v199, 0x90000, v196
	v_lshrrev_b32_e32 v170, 6, v1
	v_lshlrev_b32_e32 v170, 10, v170
	s_nop 0
	v_readfirstlane_b32 s76, v170
.Lbr_tile:
	s_and_b32 s0, s78, 3
	s_or_b32 s0, s0, s77
	s_lshl_b32 s0, s0, 8
	s_lshr_b32 s1, s78, 2
	s_lshl_b32 s1, s1, 7
	s_mul_i32 s2, s0, 0xc00
	s_add_u32 s68, s8, s2
	s_addc_u32 s69, s9, 0
	s_mul_i32 s2, s1, 0xc00
	s_add_u32 s70, s80, s2
	s_addc_u32 s71, s81, 0
	s_mul_i32 s2, s0, 0x3400
	s_lshl_b32 s3, s1, 1
	s_add_u32 s2, s2, s3
	s_add_u32 s2, s2, 0x1c00
	s_add_u32 s72, s4, s2
	s_addc_u32 s73, s5, 0
	s_lshl_b32 s2, s0, 11
	s_add_u32 s2, s2, s3
	s_add_u32 s74, s10, s2
	s_addc_u32 s75, s11, 0
	s_add_u32 m0, s76, 0x0
	s_nop 0
	global_load_lds_dwordx4 v196, s[68:69]
	s_add_u32 m0, s76, 0x2000
	s_nop 0
	global_load_lds_dwordx4 v197, s[68:69]
	s_add_u32 m0, s76, 0x4000
	s_nop 0
	global_load_lds_dwordx4 v198, s[68:69]
	s_add_u32 m0, s76, 0x6000
	s_nop 0
	global_load_lds_dwordx4 v199, s[68:69]
	s_add_u32 m0, s76, 0x8000
	s_nop 0
	global_load_lds_dwordx4 v196, s[70:71]
	s_add_u32 m0, s76, 0xa000
	s_nop 0
	global_load_lds_dwordx4 v197, s[70:71]
	s_add_u32 s68, s68, 0x80
	s_addc_u32 s69, s69, 0
	s_add_u32 s70, s70, 0x80
	s_addc_u32 s71, s71, 0
	s_add_u32 m0, s76, 0xc000
	s_nop 0
	global_load_lds_dwordx4 v196, s[68:69]
	s_add_u32 m0, s76, 0xe000
	s_nop 0
	global_load_lds_dwordx4 v197, s[68:69]
	s_add_u32 m0, s76, 0x10000
	s_nop 0
	global_load_lds_dwordx4 v198, s[68:69]
	s_add_u32 m0, s76, 0x12000
	s_nop 0
	global_load_lds_dwordx4 v199, s[68:69]
	s_add_u32 m0, s76, 0x14000
	s_nop 0
	global_load_lds_dwordx4 v196, s[70:71]
	s_add_u32 m0, s76, 0x16000
	s_nop 0
	global_load_lds_dwordx4 v197, s[70:71]
	s_add_u32 s68, s68, 0x80
	s_addc_u32 s69, s69, 0
	s_add_u32 s70, s70, 0x80
	s_addc_u32 s71, s71, 0
	v_mov_b32_e32 v66, 0
	v_mov_b32_e32 v67, 0
	v_mov_b32_e32 v68, 0
	v_mov_b32_e32 v69, 0
	v_mov_b32_e32 v70, 0
	v_mov_b32_e32 v71, 0
	v_mov_b32_e32 v72, 0
	v_mov_b32_e32 v73, 0
	v_mov_b32_e32 v74, 0
	v_mov_b32_e32 v75, 0
	v_mov_b32_e32 v76, 0
	v_mov_b32_e32 v77, 0
	v_mov_b32_e32 v78, 0
	v_mov_b32_e32 v79, 0
	v_mov_b32_e32 v80, 0
	v_mov_b32_e32 v81, 0
	v_mov_b32_e32 v82, 0
	v_mov_b32_e32 v83, 0
	v_mov_b32_e32 v84, 0
	v_mov_b32_e32 v85, 0
	v_mov_b32_e32 v86, 0
	v_mov_b32_e32 v87, 0
	v_mov_b32_e32 v88, 0
	v_mov_b32_e32 v89, 0
	v_mov_b32_e32 v90, 0
	v_mov_b32_e32 v91, 0
	v_mov_b32_e32 v92, 0
	v_mov_b32_e32 v93, 0
	v_mov_b32_e32 v94, 0
	v_mov_b32_e32 v95, 0
	v_mov_b32_e32 v96, 0
	v_mov_b32_e32 v97, 0
	v_mov_b32_e32 v98, 0
	v_mov_b32_e32 v99, 0
	v_mov_b32_e32 v100, 0
	v_mov_b32_e32 v101, 0
	v_mov_b32_e32 v102, 0
	v_mov_b32_e32 v103, 0
	v_mov_b32_e32 v104, 0
	v_mov_b32_e32 v105, 0
	v_mov_b32_e32 v106, 0
	v_mov_b32_e32 v107, 0
	v_mov_b32_e32 v108, 0
	v_mov_b32_e32 v109, 0
	v_mov_b32_e32 v110, 0
	v_mov_b32_e32 v111, 0
	v_mov_b32_e32 v112, 0
	v_mov_b32_e32 v113, 0
	v_mov_b32_e32 v114, 0
	v_mov_b32_e32 v115, 0
	v_mov_b32_e32 v116, 0
	v_mov_b32_e32 v117, 0
	v_mov_b32_e32 v118, 0
	v_mov_b32_e32 v119, 0
	v_mov_b32_e32 v120, 0
	v_mov_b32_e32 v121, 0
	v_mov_b32_e32 v122, 0
	v_mov_b32_e32 v123, 0
	v_mov_b32_e32 v124, 0
	v_mov_b32_e32 v125, 0
	v_mov_b32_e32 v126, 0
	v_mov_b32_e32 v127, 0
	v_mov_b32_e32 v128, 0
	v_mov_b32_e32 v129, 0
	s_waitcnt vmcnt(6)
	s_waitcnt lgkmcnt(0)
	s_barrier
	v_add_u32_e32 v204, 0x0, v200
	v_add_u32_e32 v205, 0x0, v202
	ds_read_b128 v[130:133], v204 offset:0
	ds_read_b128 v[134:137], v204 offset:2048
	ds_read_b128 v[138:141], v204 offset:4096
	ds_read_b128 v[142:145], v204 offset:6144
	ds_read_b128 v[146:149], v205 offset:0
	ds_read_b128 v[150:153], v205 offset:2048
	ds_read_b128 v[154:157], v205 offset:4096
	ds_read_b128 v[158:161], v205 offset:6144
	s_add_u32 m0, s76, 0x18000
	s_nop 0
	global_load_lds_dwordx4 v196, s[68:69]
	s_add_u32 m0, s76, 0x1a000
	s_nop 0
	global_load_lds_dwordx4 v197, s[68:69]
	s_add_u32 m0, s76, 0x1c000
	s_nop 0
	global_load_lds_dwordx4 v198, s[68:69]
	s_add_u32 m0, s76, 0x1e000
	s_nop 0
	global_load_lds_dwordx4 v199, s[68:69]
	s_add_u32 m0, s76, 0x20000
	s_nop 0
	global_load_lds_dwordx4 v196, s[70:71]
	s_add_u32 m0, s76, 0x22000
	s_nop 0
	global_load_lds_dwordx4 v197, s[70:71]
	s_add_u32 s68, s68, 0x80
	s_addc_u32 s69, s69, 0
	s_add_u32 s70, s70, 0x80
	s_addc_u32 s71, s71, 0
	s_waitcnt lgkmcnt(0)
	v_add_u32_e32 v204, 0x0, v201
	v_add_u32_e32 v205, 0x0, v203
	ds_read_b128 v[212:215], v204 offset:0
	ds_read_b128 v[216:219], v204 offset:2048
	ds_read_b128 v[220:223], v204 offset:4096
	ds_read_b128 v[224:227], v204 offset:6144
	ds_read_b128 v[228:231], v205 offset:0
	ds_read_b128 v[232:235], v205 offset:2048
	ds_read_b128 v[236:239], v205 offset:4096
	ds_read_b128 v[240:243], v205 offset:6144
	v_mfma_f32_16x16x32_bf16 v[2:5], v[146:149], v[130:133], 0
	v_mfma_f32_16x16x32_bf16 v[6:9], v[150:153], v[130:133], 0
	global_load_dwordx2 v[174:175], v206, s[72:73] offset:0
	v_mfma_f32_16x16x32_bf16 v[10:13], v[154:157], v[130:133], 0
	v_mfma_f32_16x16x32_bf16 v[14:17], v[158:161], v[130:133], 0
	global_load_dwordx2 v[176:177], v206, s[72:73] offset:32
	v_mfma_f32_16x16x32_bf16 v[18:21], v[146:149], v[134:137], 0
	v_mfma_f32_16x16x32_bf16 v[22:25], v[150:153], v[134:137], 0
	global_load_dwordx2 v[178:179], v206, s[72:73] offset:64
	v_mfma_f32_16x16x32_bf16 v[26:29], v[154:157], v[134:137], 0
	v_mfma_f32_16x16x32_bf16 v[30:33], v[158:161], v[134:137], 0
	global_load_dwordx2 v[180:181], v206, s[72:73] offset:96
	v_mfma_f32_16x16x32_bf16 v[34:37], v[146:149], v[138:141], 0
	v_mfma_f32_16x16x32_bf16 v[38:41], v[150:153], v[138:141], 0
	global_load_dwordx2 v[182:183], v207, s[72:73] offset:0
	v_mfma_f32_16x16x32_bf16 v[42:45], v[154:157], v[138:141], 0
	v_mfma_f32_16x16x32_bf16 v[46:49], v[158:161], v[138:141], 0
	global_load_dwordx2 v[184:185], v207, s[72:73] offset:32
	v_mfma_f32_16x16x32_bf16 v[50:53], v[146:149], v[142:145], 0
	v_mfma_f32_16x16x32_bf16 v[54:57], v[150:153], v[142:145], 0
	v_mfma_f32_16x16x32_bf16 v[58:61], v[154:157], v[142:145], 0
	v_mfma_f32_16x16x32_bf16 v[62:65], v[158:161], v[142:145], 0
	s_waitcnt vmcnt(12)
	s_waitcnt lgkmcnt(0)
	s_barrier
	v_add_u32_e32 v204, 0xc000, v200
	v_add_u32_e32 v205, 0xc000, v202
	ds_read_b128 v[130:133], v204 offset:0
	ds_read_b128 v[134:137], v204 offset:2048
	ds_read_b128 v[138:141], v204 offset:4096
	ds_read_b128 v[142:145], v204 offset:6144
	ds_read_b128 v[146:149], v205 offset:0
	ds_read_b128 v[150:153], v205 offset:2048
	ds_read_b128 v[154:157], v205 offset:4096
	ds_read_b128 v[158:161], v205 offset:6144
	v_mfma_f32_16x16x32_bf16 v[2:5], v[228:231], v[212:215], v[2:5]
	v_mfma_f32_16x16x32_bf16 v[6:9], v[232:235], v[212:215], v[6:9]
	s_add_u32 m0, s76, 0x0
	s_nop 0
	global_load_lds_dwordx4 v196, s[68:69]
	v_mfma_f32_16x16x32_bf16 v[10:13], v[236:239], v[212:215], v[10:13]
	v_mfma_f32_16x16x32_bf16 v[14:17], v[240:243], v[212:215], v[14:17]
	s_add_u32 m0, s76, 0x2000
	s_nop 0
	global_load_lds_dwordx4 v197, s[68:69]
	v_mfma_f32_16x16x32_bf16 v[18:21], v[228:231], v[216:219], v[18:21]
	v_mfma_f32_16x16x32_bf16 v[22:25], v[232:235], v[216:219], v[22:25]
	s_add_u32 m0, s76, 0x4000
	s_nop 0
	global_load_lds_dwordx4 v198, s[68:69]
	v_mfma_f32_16x16x32_bf16 v[26:29], v[236:239], v[216:219], v[26:29]
	v_mfma_f32_16x16x32_bf16 v[30:33], v[240:243], v[216:219], v[30:33]
	s_add_u32 m0, s76, 0x6000
	s_nop 0
	global_load_lds_dwordx4 v199, s[68:69]
	v_mfma_f32_16x16x32_bf16 v[34:37], v[228:231], v[220:223], v[34:37]
	v_mfma_f32_16x16x32_bf16 v[38:41], v[232:235], v[220:223], v[38:41]
	s_add_u32 m0, s76, 0x8000
	s_nop 0
	global_load_lds_dwordx4 v196, s[70:71]
	v_mfma_f32_16x16x32_bf16 v[42:45], v[236:239], v[220:223], v[42:45]
	v_mfma_f32_16x16x32_bf16 v[46:49], v[240:243], v[220:223], v[46:49]
	s_add_u32 m0, s76, 0xa000
	s_nop 0
	global_load_lds_dwordx4 v197, s[70:71]
	v_mfma_f32_16x16x32_bf16 v[50:53], v[228:231], v[224:227], v[50:53]
	v_mfma_f32_16x16x32_bf16 v[54:57], v[232:235], v[224:227], v[54:57]
	s_add_u32 s68, s68, 0x80
	s_addc_u32 s69, s69, 0
	s_add_u32 s70, s70, 0x80
	s_addc_u32 s71, s71, 0
	v_mfma_f32_16x16x32_bf16 v[58:61], v[236:239], v[224:227], v[58:61]
	v_mfma_f32_16x16x32_bf16 v[62:65], v[240:243], v[224:227], v[62:65]
	s_waitcnt lgkmcnt(0)
	v_add_u32_e32 v204, 0xc000, v201
	v_add_u32_e32 v205, 0xc000, v203
	ds_read_b128 v[212:215], v204 offset:0
	ds_read_b128 v[216:219], v204 offset:2048
	ds_read_b128 v[220:223], v204 offset:4096
	ds_read_b128 v[224:227], v204 offset:6144
	ds_read_b128 v[228:231], v205 offset:0
	ds_read_b128 v[232:235], v205 offset:2048
	ds_read_b128 v[236:239], v205 offset:4096
	ds_read_b128 v[240:243], v205 offset:6144
	v_mfma_f32_16x16x32_bf16 v[2:5], v[146:149], v[130:133], v[2:5]
	v_mfma_f32_16x16x32_bf16 v[6:9], v[150:153], v[130:133], v[6:9]
	global_load_dwordx2 v[186:187], v207, s[72:73] offset:64
	v_mfma_f32_16x16x32_bf16 v[10:13], v[154:157], v[130:133], v[10:13]
	v_mfma_f32_16x16x32_bf16 v[14:17], v[158:161], v[130:133], v[14:17]
	global_load_dwordx2 v[188:189], v207, s[72:73] offset:96
	v_mfma_f32_16x16x32_bf16 v[18:21], v[146:149], v[134:137], v[18:21]
	v_mfma_f32_16x16x32_bf16 v[22:25], v[150:153], v[134:137], v[22:25]
	global_load_dwordx2 v[190:191], v208, s[72:73] offset:0
	v_mfma_f32_16x16x32_bf16 v[26:29], v[154:157], v[134:137], v[26:29]
	v_mfma_f32_16x16x32_bf16 v[30:33], v[158:161], v[134:137], v[30:33]
	global_load_dwordx2 v[192:193], v208, s[72:73] offset:32
	v_mfma_f32_16x16x32_bf16 v[34:37], v[146:149], v[138:141], v[34:37]
	v_mfma_f32_16x16x32_bf16 v[38:41], v[150:153], v[138:141], v[38:41]
	global_load_dwordx2 v[244:245], v208, s[72:73] offset:64
	v_mfma_f32_16x16x32_bf16 v[42:45], v[154:157], v[138:141], v[42:45]
	v_mfma_f32_16x16x32_bf16 v[46:49], v[158:161], v[138:141], v[46:49]
	global_load_dwordx2 v[246:247], v208, s[72:73] offset:96
	v_mfma_f32_16x16x32_bf16 v[50:53], v[146:149], v[142:145], v[50:53]
	v_mfma_f32_16x16x32_bf16 v[54:57], v[150:153], v[142:145], v[54:57]
	v_mfma_f32_16x16x32_bf16 v[58:61], v[154:157], v[142:145], v[58:61]
	v_mfma_f32_16x16x32_bf16 v[62:65], v[158:161], v[142:145], v[62:65]
	s_waitcnt vmcnt(18)
	s_waitcnt lgkmcnt(0)
	s_barrier
	v_add_u32_e32 v204, 0x18000, v200
	v_add_u32_e32 v205, 0x18000, v202
	ds_read_b128 v[130:133], v204 offset:0
	ds_read_b128 v[134:137], v204 offset:2048
	ds_read_b128 v[138:141], v204 offset:4096
	ds_read_b128 v[142:145], v204 offset:6144
	ds_read_b128 v[146:149], v205 offset:0
	ds_read_b128 v[150:153], v205 offset:2048
	ds_read_b128 v[154:157], v205 offset:4096
	ds_read_b128 v[158:161], v205 offset:6144
	v_mfma_f32_16x16x32_bf16 v[2:5], v[228:231], v[212:215], v[2:5]
	v_mfma_f32_16x16x32_bf16 v[6:9], v[232:235], v[212:215], v[6:9]
	s_add_u32 m0, s76, 0xc000
	s_nop 0
	global_load_lds_dwordx4 v196, s[68:69]
	v_mfma_f32_16x16x32_bf16 v[10:13], v[236:239], v[212:215], v[10:13]
	v_mfma_f32_16x16x32_bf16 v[14:17], v[240:243], v[212:215], v[14:17]
	s_add_u32 m0, s76, 0xe000
	s_nop 0
	global_load_lds_dwordx4 v197, s[68:69]
	v_mfma_f32_16x16x32_bf16 v[18:21], v[228:231], v[216:219], v[18:21]
	v_mfma_f32_16x16x32_bf16 v[22:25], v[232:235], v[216:219], v[22:25]
	s_add_u32 m0, s76, 0x10000
	s_nop 0
	global_load_lds_dwordx4 v198, s[68:69]
	v_mfma_f32_16x16x32_bf16 v[26:29], v[236:239], v[216:219], v[26:29]
	v_mfma_f32_16x16x32_bf16 v[30:33], v[240:243], v[216:219], v[30:33]
	s_add_u32 m0, s76, 0x12000
	s_nop 0
	global_load_lds_dwordx4 v199, s[68:69]
	v_mfma_f32_16x16x32_bf16 v[34:37], v[228:231], v[220:223], v[34:37]
	v_mfma_f32_16x16x32_bf16 v[38:41], v[232:235], v[220:223], v[38:41]
	s_add_u32 m0, s76, 0x14000
	s_nop 0
	global_load_lds_dwordx4 v196, s[70:71]
	v_mfma_f32_16x16x32_bf16 v[42:45], v[236:239], v[220:223], v[42:45]
	v_mfma_f32_16x16x32_bf16 v[46:49], v[240:243], v[220:223], v[46:49]
	s_add_u32 m0, s76, 0x16000
	s_nop 0
	global_load_lds_dwordx4 v197, s[70:71]
	v_mfma_f32_16x16x32_bf16 v[50:53], v[228:231], v[224:227], v[50:53]
	v_mfma_f32_16x16x32_bf16 v[54:57], v[232:235], v[224:227], v[54:57]
	s_add_u32 s68, s68, 0x80
	s_addc_u32 s69, s69, 0
	s_add_u32 s70, s70, 0x80
	s_addc_u32 s71, s71, 0
	v_mfma_f32_16x16x32_bf16 v[58:61], v[236:239], v[224:227], v[58:61]
	v_mfma_f32_16x16x32_bf16 v[62:65], v[240:243], v[224:227], v[62:65]
	s_waitcnt lgkmcnt(0)
	v_add_u32_e32 v204, 0x18000, v201
	v_add_u32_e32 v205, 0x18000, v203
	ds_read_b128 v[212:215], v204 offset:0
	ds_read_b128 v[216:219], v204 offset:2048
	ds_read_b128 v[220:223], v204 offset:4096
	ds_read_b128 v[224:227], v204 offset:6144
	ds_read_b128 v[228:231], v205 offset:0
	ds_read_b128 v[232:235], v205 offset:2048
	ds_read_b128 v[236:239], v205 offset:4096
	ds_read_b128 v[240:243], v205 offset:6144
	v_mfma_f32_16x16x32_bf16 v[2:5], v[146:149], v[130:133], v[2:5]
	v_mfma_f32_16x16x32_bf16 v[6:9], v[150:153], v[130:133], v[6:9]
	global_load_dwordx2 v[248:249], v209, s[72:73] offset:0
	v_mfma_f32_16x16x32_bf16 v[10:13], v[154:157], v[130:133], v[10:13]
	v_mfma_f32_16x16x32_bf16 v[14:17], v[158:161], v[130:133], v[14:17]
	global_load_dwordx2 v[250:251], v209, s[72:73] offset:32
	v_mfma_f32_16x16x32_bf16 v[18:21], v[146:149], v[134:137], v[18:21]
	v_mfma_f32_16x16x32_bf16 v[22:25], v[150:153], v[134:137], v[22:25]
	global_load_dwordx2 v[166:167], v209, s[72:73] offset:64
	v_mfma_f32_16x16x32_bf16 v[26:29], v[154:157], v[134:137], v[26:29]
	v_mfma_f32_16x16x32_bf16 v[30:33], v[158:161], v[134:137], v[30:33]
	global_load_dwordx2 v[194:195], v209, s[72:73] offset:96
	v_mfma_f32_16x16x32_bf16 v[34:37], v[146:149], v[138:141], v[34:37]
	v_mfma_f32_16x16x32_bf16 v[38:41], v[150:153], v[138:141], v[38:41]
	s_add_u32 s72, s72, 0x800
	s_addc_u32 s73, s73, 0
	v_mfma_f32_16x16x32_bf16 v[42:45], v[154:157], v[138:141], v[42:45]
	v_mfma_f32_16x16x32_bf16 v[46:49], v[158:161], v[138:141], v[46:49]
	v_mfma_f32_16x16x32_bf16 v[50:53], v[146:149], v[142:145], v[50:53]
	v_mfma_f32_16x16x32_bf16 v[54:57], v[150:153], v[142:145], v[54:57]
	v_mfma_f32_16x16x32_bf16 v[58:61], v[154:157], v[142:145], v[58:61]
	v_mfma_f32_16x16x32_bf16 v[62:65], v[158:161], v[142:145], v[62:65]
	s_waitcnt vmcnt(16)
	s_waitcnt lgkmcnt(0)
	s_barrier
	v_add_u32_e32 v204, 0x0, v200
	v_add_u32_e32 v205, 0x0, v202
	ds_read_b128 v[130:133], v204 offset:0
	ds_read_b128 v[134:137], v204 offset:2048
	ds_read_b128 v[138:141], v204 offset:4096
	ds_read_b128 v[142:145], v204 offset:6144
	ds_read_b128 v[146:149], v205 offset:0
	ds_read_b128 v[150:153], v205 offset:2048
	ds_read_b128 v[154:157], v205 offset:4096
	ds_read_b128 v[158:161], v205 offset:6144
	v_mfma_f32_16x16x32_bf16 v[2:5], v[228:231], v[212:215], v[2:5]
	v_mfma_f32_16x16x32_bf16 v[6:9], v[232:235], v[212:215], v[6:9]
	s_add_u32 m0, s76, 0x18000
	s_nop 0
	global_load_lds_dwordx4 v196, s[68:69]
	v_mfma_f32_16x16x32_bf16 v[10:13], v[236:239], v[212:215], v[10:13]
	v_mfma_f32_16x16x32_bf16 v[14:17], v[240:243], v[212:215], v[14:17]
	s_add_u32 m0, s76, 0x1a000
	s_nop 0
	global_load_lds_dwordx4 v197, s[68:69]
	v_mfma_f32_16x16x32_bf16 v[18:21], v[228:231], v[216:219], v[18:21]
	v_mfma_f32_16x16x32_bf16 v[22:25], v[232:235], v[216:219], v[22:25]
	s_add_u32 m0, s76, 0x1c000
	s_nop 0
	global_load_lds_dwordx4 v198, s[68:69]
	v_mfma_f32_16x16x32_bf16 v[26:29], v[236:239], v[216:219], v[26:29]
	v_mfma_f32_16x16x32_bf16 v[30:33], v[240:243], v[216:219], v[30:33]
	s_add_u32 m0, s76, 0x1e000
	s_nop 0
	global_load_lds_dwordx4 v199, s[68:69]
	v_mfma_f32_16x16x32_bf16 v[34:37], v[228:231], v[220:223], v[34:37]
	v_mfma_f32_16x16x32_bf16 v[38:41], v[232:235], v[220:223], v[38:41]
	s_add_u32 m0, s76, 0x20000
	s_nop 0
	global_load_lds_dwordx4 v196, s[70:71]
	v_mfma_f32_16x16x32_bf16 v[42:45], v[236:239], v[220:223], v[42:45]
	v_mfma_f32_16x16x32_bf16 v[46:49], v[240:243], v[220:223], v[46:49]
	s_add_u32 m0, s76, 0x22000
	s_nop 0
	global_load_lds_dwordx4 v197, s[70:71]
	v_mfma_f32_16x16x32_bf16 v[50:53], v[228:231], v[224:227], v[50:53]
	v_mfma_f32_16x16x32_bf16 v[54:57], v[232:235], v[224:227], v[54:57]
	s_add_u32 s68, s68, 0x80
	s_addc_u32 s69, s69, 0
	s_add_u32 s70, s70, 0x80
	s_addc_u32 s71, s71, 0
	v_mfma_f32_16x16x32_bf16 v[58:61], v[236:239], v[224:227], v[58:61]
	v_mfma_f32_16x16x32_bf16 v[62:65], v[240:243], v[224:227], v[62:65]
	s_waitcnt lgkmcnt(0)
	v_add_u32_e32 v204, 0x0, v201
	v_add_u32_e32 v205, 0x0, v203
	ds_read_b128 v[212:215], v204 offset:0
	ds_read_b128 v[216:219], v204 offset:2048
	ds_read_b128 v[220:223], v204 offset:4096
	ds_read_b128 v[224:227], v204 offset:6144
	ds_read_b128 v[228:231], v205 offset:0
	ds_read_b128 v[232:235], v205 offset:2048
	ds_read_b128 v[236:239], v205 offset:4096
	ds_read_b128 v[240:243], v205 offset:6144
	v_mfma_f32_16x16x32_bf16 v[2:5], v[146:149], v[130:133], v[2:5]
	v_mfma_f32_16x16x32_bf16 v[6:9], v[150:153], v[130:133], v[6:9]
	v_mfma_f32_16x16x32_bf16 v[10:13], v[154:157], v[130:133], v[10:13]
	v_mfma_f32_16x16x32_bf16 v[14:17], v[158:161], v[130:133], v[14:17]
	v_mfma_f32_16x16x32_bf16 v[18:21], v[146:149], v[134:137], v[18:21]
	v_mfma_f32_16x16x32_bf16 v[22:25], v[150:153], v[134:137], v[22:25]
	v_mfma_f32_16x16x32_bf16 v[26:29], v[154:157], v[134:137], v[26:29]
	v_mfma_f32_16x16x32_bf16 v[30:33], v[158:161], v[134:137], v[30:33]
	v_mfma_f32_16x16x32_bf16 v[34:37], v[146:149], v[138:141], v[34:37]
	v_mfma_f32_16x16x32_bf16 v[38:41], v[150:153], v[138:141], v[38:41]
	v_mfma_f32_16x16x32_bf16 v[42:45], v[154:157], v[138:141], v[42:45]
	v_mfma_f32_16x16x32_bf16 v[46:49], v[158:161], v[138:141], v[46:49]
	v_mfma_f32_16x16x32_bf16 v[50:53], v[146:149], v[142:145], v[50:53]
	v_mfma_f32_16x16x32_bf16 v[54:57], v[150:153], v[142:145], v[54:57]
	v_mfma_f32_16x16x32_bf16 v[58:61], v[154:157], v[142:145], v[58:61]
	v_mfma_f32_16x16x32_bf16 v[62:65], v[158:161], v[142:145], v[62:65]
	s_waitcnt vmcnt(10)
	s_waitcnt lgkmcnt(0)
	s_barrier
	v_add_u32_e32 v204, 0xc000, v200
	v_add_u32_e32 v205, 0xc000, v202
	ds_read_b128 v[130:133], v204 offset:0
	ds_read_b128 v[134:137], v204 offset:2048
	ds_read_b128 v[138:141], v204 offset:4096
	ds_read_b128 v[142:145], v204 offset:6144
	ds_read_b128 v[146:149], v205 offset:0
	ds_read_b128 v[150:153], v205 offset:2048
	ds_read_b128 v[154:157], v205 offset:4096
	ds_read_b128 v[158:161], v205 offset:6144
	v_mfma_f32_16x16x32_bf16 v[2:5], v[228:231], v[212:215], v[2:5]
	v_mfma_f32_16x16x32_bf16 v[6:9], v[232:235], v[212:215], v[6:9]
	s_add_u32 m0, s76, 0x0
	s_nop 0
	global_load_lds_dwordx4 v196, s[68:69]
	v_mfma_f32_16x16x32_bf16 v[10:13], v[236:239], v[212:215], v[10:13]
	v_mfma_f32_16x16x32_bf16 v[14:17], v[240:243], v[212:215], v[14:17]
	s_add_u32 m0, s76, 0x2000
	s_nop 0
	global_load_lds_dwordx4 v197, s[68:69]
	v_mfma_f32_16x16x32_bf16 v[18:21], v[228:231], v[216:219], v[18:21]
	v_mfma_f32_16x16x32_bf16 v[22:25], v[232:235], v[216:219], v[22:25]
	s_add_u32 m0, s76, 0x4000
	s_nop 0
	global_load_lds_dwordx4 v198, s[68:69]
	v_mfma_f32_16x16x32_bf16 v[26:29], v[236:239], v[216:219], v[26:29]
	v_mfma_f32_16x16x32_bf16 v[30:33], v[240:243], v[216:219], v[30:33]
	s_add_u32 m0, s76, 0x6000
	s_nop 0
	global_load_lds_dwordx4 v199, s[68:69]
	v_mfma_f32_16x16x32_bf16 v[34:37], v[228:231], v[220:223], v[34:37]
	v_mfma_f32_16x16x32_bf16 v[38:41], v[232:235], v[220:223], v[38:41]
	s_add_u32 m0, s76, 0x8000
	s_nop 0
	global_load_lds_dwordx4 v196, s[70:71]
	v_mfma_f32_16x16x32_bf16 v[42:45], v[236:239], v[220:223], v[42:45]
	v_mfma_f32_16x16x32_bf16 v[46:49], v[240:243], v[220:223], v[46:49]
	s_add_u32 m0, s76, 0xa000
	s_nop 0
	global_load_lds_dwordx4 v197, s[70:71]
	v_mfma_f32_16x16x32_bf16 v[50:53], v[228:231], v[224:227], v[50:53]
	v_mfma_f32_16x16x32_bf16 v[54:57], v[232:235], v[224:227], v[54:57]
	s_add_u32 s68, s68, 0x80
	s_addc_u32 s69, s69, 0
	s_add_u32 s70, s70, 0x80
	s_addc_u32 s71, s71, 0
	v_mfma_f32_16x16x32_bf16 v[58:61], v[236:239], v[224:227], v[58:61]
	v_mfma_f32_16x16x32_bf16 v[62:65], v[240:243], v[224:227], v[62:65]
	s_waitcnt lgkmcnt(0)
	v_add_u32_e32 v204, 0xc000, v201
	v_add_u32_e32 v205, 0xc000, v203
	ds_read_b128 v[212:215], v204 offset:0
	ds_read_b128 v[216:219], v204 offset:2048
	ds_read_b128 v[220:223], v204 offset:4096
	ds_read_b128 v[224:227], v204 offset:6144
	ds_read_b128 v[228:231], v205 offset:0
	ds_read_b128 v[232:235], v205 offset:2048
	ds_read_b128 v[236:239], v205 offset:4096
	ds_read_b128 v[240:243], v205 offset:6144
	v_mfma_f32_16x16x32_bf16 v[2:5], v[146:149], v[130:133], v[2:5]
	v_mfma_f32_16x16x32_bf16 v[6:9], v[150:153], v[130:133], v[6:9]
	v_mfma_f32_16x16x32_bf16 v[10:13], v[154:157], v[130:133], v[10:13]
	v_mfma_f32_16x16x32_bf16 v[14:17], v[158:161], v[130:133], v[14:17]
	v_mfma_f32_16x16x32_bf16 v[18:21], v[146:149], v[134:137], v[18:21]
	v_mfma_f32_16x16x32_bf16 v[22:25], v[150:153], v[134:137], v[22:25]
	v_mfma_f32_16x16x32_bf16 v[26:29], v[154:157], v[134:137], v[26:29]
	v_mfma_f32_16x16x32_bf16 v[30:33], v[158:161], v[134:137], v[30:33]
	v_mfma_f32_16x16x32_bf16 v[34:37], v[146:149], v[138:141], v[34:37]
	v_mfma_f32_16x16x32_bf16 v[38:41], v[150:153], v[138:141], v[38:41]
	v_mfma_f32_16x16x32_bf16 v[42:45], v[154:157], v[138:141], v[42:45]
	v_mfma_f32_16x16x32_bf16 v[46:49], v[158:161], v[138:141], v[46:49]
	v_mfma_f32_16x16x32_bf16 v[50:53], v[146:149], v[142:145], v[50:53]
	v_mfma_f32_16x16x32_bf16 v[54:57], v[150:153], v[142:145], v[54:57]
	v_mfma_f32_16x16x32_bf16 v[58:61], v[154:157], v[142:145], v[58:61]
	v_mfma_f32_16x16x32_bf16 v[62:65], v[158:161], v[142:145], v[62:65]
	s_waitcnt vmcnt(6)
	s_waitcnt lgkmcnt(0)
	s_barrier
	v_add_u32_e32 v204, 0x18000, v200
	v_add_u32_e32 v205, 0x18000, v202
	ds_read_b128 v[130:133], v204 offset:0
	ds_read_b128 v[134:137], v204 offset:2048
	ds_read_b128 v[138:141], v204 offset:4096
	ds_read_b128 v[142:145], v204 offset:6144
	ds_read_b128 v[146:149], v205 offset:0
	ds_read_b128 v[150:153], v205 offset:2048
	ds_read_b128 v[154:157], v205 offset:4096
	ds_read_b128 v[158:161], v205 offset:6144
	v_mfma_f32_16x16x32_bf16 v[2:5], v[228:231], v[212:215], v[2:5]
	v_mfma_f32_16x16x32_bf16 v[6:9], v[232:235], v[212:215], v[6:9]
	s_add_u32 m0, s76, 0xc000
	s_nop 0
	global_load_lds_dwordx4 v196, s[68:69]
	v_mfma_f32_16x16x32_bf16 v[10:13], v[236:239], v[212:215], v[10:13]
	v_mfma_f32_16x16x32_bf16 v[14:17], v[240:243], v[212:215], v[14:17]
	s_add_u32 m0, s76, 0xe000
	s_nop 0
	global_load_lds_dwordx4 v197, s[68:69]
	v_mfma_f32_16x16x32_bf16 v[18:21], v[228:231], v[216:219], v[18:21]
	v_mfma_f32_16x16x32_bf16 v[22:25], v[232:235], v[216:219], v[22:25]
	s_add_u32 m0, s76, 0x10000
	s_nop 0
	global_load_lds_dwordx4 v198, s[68:69]
	v_mfma_f32_16x16x32_bf16 v[26:29], v[236:239], v[216:219], v[26:29]
	v_mfma_f32_16x16x32_bf16 v[30:33], v[240:243], v[216:219], v[30:33]
	s_add_u32 m0, s76, 0x12000
	s_nop 0
	global_load_lds_dwordx4 v199, s[68:69]
	v_mfma_f32_16x16x32_bf16 v[34:37], v[228:231], v[220:223], v[34:37]
	v_mfma_f32_16x16x32_bf16 v[38:41], v[232:235], v[220:223], v[38:41]
	s_add_u32 m0, s76, 0x14000
	s_nop 0
	global_load_lds_dwordx4 v196, s[70:71]
	v_mfma_f32_16x16x32_bf16 v[42:45], v[236:239], v[220:223], v[42:45]
	v_mfma_f32_16x16x32_bf16 v[46:49], v[240:243], v[220:223], v[46:49]
	s_add_u32 m0, s76, 0x16000
	s_nop 0
	global_load_lds_dwordx4 v197, s[70:71]
	v_mfma_f32_16x16x32_bf16 v[50:53], v[228:231], v[224:227], v[50:53]
	v_mfma_f32_16x16x32_bf16 v[54:57], v[232:235], v[224:227], v[54:57]
	s_add_u32 s68, s68, 0x80
	s_addc_u32 s69, s69, 0
	s_add_u32 s70, s70, 0x80
	s_addc_u32 s71, s71, 0
	v_mfma_f32_16x16x32_bf16 v[58:61], v[236:239], v[224:227], v[58:61]
	v_mfma_f32_16x16x32_bf16 v[62:65], v[240:243], v[224:227], v[62:65]
	s_waitcnt lgkmcnt(0)
	v_add_u32_e32 v204, 0x18000, v201
	v_add_u32_e32 v205, 0x18000, v203
	ds_read_b128 v[212:215], v204 offset:0
	ds_read_b128 v[216:219], v204 offset:2048
	ds_read_b128 v[220:223], v204 offset:4096
	ds_read_b128 v[224:227], v204 offset:6144
	ds_read_b128 v[228:231], v205 offset:0
	ds_read_b128 v[232:235], v205 offset:2048
	ds_read_b128 v[236:239], v205 offset:4096
	ds_read_b128 v[240:243], v205 offset:6144
	v_mfma_f32_16x16x32_bf16 v[2:5], v[146:149], v[130:133], v[2:5]
	v_mfma_f32_16x16x32_bf16 v[6:9], v[150:153], v[130:133], v[6:9]
	v_mfma_f32_16x16x32_bf16 v[10:13], v[154:157], v[130:133], v[10:13]
	v_mfma_f32_16x16x32_bf16 v[14:17], v[158:161], v[130:133], v[14:17]
	v_mfma_f32_16x16x32_bf16 v[18:21], v[146:149], v[134:137], v[18:21]
	v_mfma_f32_16x16x32_bf16 v[22:25], v[150:153], v[134:137], v[22:25]
	v_mfma_f32_16x16x32_bf16 v[26:29], v[154:157], v[134:137], v[26:29]
	v_mfma_f32_16x16x32_bf16 v[30:33], v[158:161], v[134:137], v[30:33]
	v_mfma_f32_16x16x32_bf16 v[34:37], v[146:149], v[138:141], v[34:37]
	v_mfma_f32_16x16x32_bf16 v[38:41], v[150:153], v[138:141], v[38:41]
	v_mfma_f32_16x16x32_bf16 v[42:45], v[154:157], v[138:141], v[42:45]
	v_mfma_f32_16x16x32_bf16 v[46:49], v[158:161], v[138:141], v[46:49]
	v_mfma_f32_16x16x32_bf16 v[50:53], v[146:149], v[142:145], v[50:53]
	v_mfma_f32_16x16x32_bf16 v[54:57], v[150:153], v[142:145], v[54:57]
	v_mfma_f32_16x16x32_bf16 v[58:61], v[154:157], v[142:145], v[58:61]
	v_mfma_f32_16x16x32_bf16 v[62:65], v[158:161], v[142:145], v[62:65]
	s_waitcnt vmcnt(6)
	s_waitcnt lgkmcnt(0)
	s_barrier
	v_add_u32_e32 v204, 0x0, v200
	v_add_u32_e32 v205, 0x0, v202
	ds_read_b128 v[130:133], v204 offset:0
	ds_read_b128 v[134:137], v204 offset:2048
	ds_read_b128 v[138:141], v204 offset:4096
	ds_read_b128 v[142:145], v204 offset:6144
	ds_read_b128 v[146:149], v205 offset:0
	ds_read_b128 v[150:153], v205 offset:2048
	ds_read_b128 v[154:157], v205 offset:4096
	ds_read_b128 v[158:161], v205 offset:6144
	v_mfma_f32_16x16x32_bf16 v[2:5], v[228:231], v[212:215], v[2:5]
	v_mfma_f32_16x16x32_bf16 v[6:9], v[232:235], v[212:215], v[6:9]
	s_add_u32 m0, s76, 0x18000
	s_nop 0
	global_load_lds_dwordx4 v196, s[68:69]
	v_mfma_f32_16x16x32_bf16 v[10:13], v[236:239], v[212:215], v[10:13]
	v_mfma_f32_16x16x32_bf16 v[14:17], v[240:243], v[212:215], v[14:17]
	s_add_u32 m0, s76, 0x1a000
	s_nop 0
	global_load_lds_dwordx4 v197, s[68:69]
	v_mfma_f32_16x16x32_bf16 v[18:21], v[228:231], v[216:219], v[18:21]
	v_mfma_f32_16x16x32_bf16 v[22:25], v[232:235], v[216:219], v[22:25]
	s_add_u32 m0, s76, 0x1c000
	s_nop 0
	global_load_lds_dwordx4 v198, s[68:69]
	v_mfma_f32_16x16x32_bf16 v[26:29], v[236:239], v[216:219], v[26:29]
	v_mfma_f32_16x16x32_bf16 v[30:33], v[240:243], v[216:219], v[30:33]
	s_add_u32 m0, s76, 0x1e000
	s_nop 0
	global_load_lds_dwordx4 v199, s[68:69]
	v_mfma_f32_16x16x32_bf16 v[34:37], v[228:231], v[220:223], v[34:37]
	v_mfma_f32_16x16x32_bf16 v[38:41], v[232:235], v[220:223], v[38:41]
	s_add_u32 m0, s76, 0x20000
	s_nop 0
	global_load_lds_dwordx4 v196, s[70:71]
	v_mfma_f32_16x16x32_bf16 v[42:45], v[236:239], v[220:223], v[42:45]
	v_mfma_f32_16x16x32_bf16 v[46:49], v[240:243], v[220:223], v[46:49]
	s_add_u32 m0, s76, 0x22000
	s_nop 0
	global_load_lds_dwordx4 v197, s[70:71]
	v_mfma_f32_16x16x32_bf16 v[50:53], v[228:231], v[224:227], v[50:53]
	v_mfma_f32_16x16x32_bf16 v[54:57], v[232:235], v[224:227], v[54:57]
	s_add_u32 s68, s68, 0x80
	s_addc_u32 s69, s69, 0
	s_add_u32 s70, s70, 0x80
	s_addc_u32 s71, s71, 0
	v_mfma_f32_16x16x32_bf16 v[58:61], v[236:239], v[224:227], v[58:61]
	v_mfma_f32_16x16x32_bf16 v[62:65], v[240:243], v[224:227], v[62:65]
	s_waitcnt lgkmcnt(0)
	v_add_u32_e32 v204, 0x0, v201
	v_add_u32_e32 v205, 0x0, v203
	ds_read_b128 v[212:215], v204 offset:0
	ds_read_b128 v[216:219], v204 offset:2048
	ds_read_b128 v[220:223], v204 offset:4096
	ds_read_b128 v[224:227], v204 offset:6144
	ds_read_b128 v[228:231], v205 offset:0
	ds_read_b128 v[232:235], v205 offset:2048
	ds_read_b128 v[236:239], v205 offset:4096
	ds_read_b128 v[240:243], v205 offset:6144
	v_mfma_f32_16x16x32_bf16 v[2:5], v[146:149], v[130:133], v[2:5]
	v_mfma_f32_16x16x32_bf16 v[6:9], v[150:153], v[130:133], v[6:9]
	v_mfma_f32_16x16x32_bf16 v[10:13], v[154:157], v[130:133], v[10:13]
	v_mfma_f32_16x16x32_bf16 v[14:17], v[158:161], v[130:133], v[14:17]
	v_mfma_f32_16x16x32_bf16 v[18:21], v[146:149], v[134:137], v[18:21]
	v_mfma_f32_16x16x32_bf16 v[22:25], v[150:153], v[134:137], v[22:25]
	v_mfma_f32_16x16x32_bf16 v[26:29], v[154:157], v[134:137], v[26:29]
	v_mfma_f32_16x16x32_bf16 v[30:33], v[158:161], v[134:137], v[30:33]
	v_mfma_f32_16x16x32_bf16 v[34:37], v[146:149], v[138:141], v[34:37]
	v_mfma_f32_16x16x32_bf16 v[38:41], v[150:153], v[138:141], v[38:41]
	v_mfma_f32_16x16x32_bf16 v[42:45], v[154:157], v[138:141], v[42:45]
	v_mfma_f32_16x16x32_bf16 v[46:49], v[158:161], v[138:141], v[46:49]
	v_mfma_f32_16x16x32_bf16 v[50:53], v[146:149], v[142:145], v[50:53]
	v_mfma_f32_16x16x32_bf16 v[54:57], v[150:153], v[142:145], v[54:57]
	v_mfma_f32_16x16x32_bf16 v[58:61], v[154:157], v[142:145], v[58:61]
	v_mfma_f32_16x16x32_bf16 v[62:65], v[158:161], v[142:145], v[62:65]
	s_waitcnt vmcnt(6)
	s_waitcnt lgkmcnt(0)
	s_barrier
	v_add_u32_e32 v204, 0xc000, v200
	v_add_u32_e32 v205, 0xc000, v202
	ds_read_b128 v[130:133], v204 offset:0
	ds_read_b128 v[134:137], v204 offset:2048
	ds_read_b128 v[138:141], v204 offset:4096
	ds_read_b128 v[142:145], v204 offset:6144
	ds_read_b128 v[146:149], v205 offset:0
	ds_read_b128 v[150:153], v205 offset:2048
	ds_read_b128 v[154:157], v205 offset:4096
	ds_read_b128 v[158:161], v205 offset:6144
	v_mfma_f32_16x16x32_bf16 v[2:5], v[228:231], v[212:215], v[2:5]
	v_mfma_f32_16x16x32_bf16 v[6:9], v[232:235], v[212:215], v[6:9]
	s_add_u32 m0, s76, 0x0
	s_nop 0
	global_load_lds_dwordx4 v196, s[68:69]
	v_mfma_f32_16x16x32_bf16 v[10:13], v[236:239], v[212:215], v[10:13]
	v_mfma_f32_16x16x32_bf16 v[14:17], v[240:243], v[212:215], v[14:17]
	s_add_u32 m0, s76, 0x2000
	s_nop 0
	global_load_lds_dwordx4 v197, s[68:69]
	v_mfma_f32_16x16x32_bf16 v[18:21], v[228:231], v[216:219], v[18:21]
	v_mfma_f32_16x16x32_bf16 v[22:25], v[232:235], v[216:219], v[22:25]
	s_add_u32 m0, s76, 0x4000
	s_nop 0
	global_load_lds_dwordx4 v198, s[68:69]
	v_mfma_f32_16x16x32_bf16 v[26:29], v[236:239], v[216:219], v[26:29]
	v_mfma_f32_16x16x32_bf16 v[30:33], v[240:243], v[216:219], v[30:33]
	s_add_u32 m0, s76, 0x6000
	s_nop 0
	global_load_lds_dwordx4 v199, s[68:69]
	v_mfma_f32_16x16x32_bf16 v[34:37], v[228:231], v[220:223], v[34:37]
	v_mfma_f32_16x16x32_bf16 v[38:41], v[232:235], v[220:223], v[38:41]
	s_add_u32 m0, s76, 0x8000
	s_nop 0
	global_load_lds_dwordx4 v196, s[70:71]
	v_mfma_f32_16x16x32_bf16 v[42:45], v[236:239], v[220:223], v[42:45]
	v_mfma_f32_16x16x32_bf16 v[46:49], v[240:243], v[220:223], v[46:49]
	s_add_u32 m0, s76, 0xa000
	s_nop 0
	global_load_lds_dwordx4 v197, s[70:71]
	v_mfma_f32_16x16x32_bf16 v[50:53], v[228:231], v[224:227], v[50:53]
	v_mfma_f32_16x16x32_bf16 v[54:57], v[232:235], v[224:227], v[54:57]
	s_add_u32 s68, s68, 0x80
	s_addc_u32 s69, s69, 0
	s_add_u32 s70, s70, 0x80
	s_addc_u32 s71, s71, 0
	v_mfma_f32_16x16x32_bf16 v[58:61], v[236:239], v[224:227], v[58:61]
	v_mfma_f32_16x16x32_bf16 v[62:65], v[240:243], v[224:227], v[62:65]
	s_waitcnt lgkmcnt(0)
	v_add_u32_e32 v204, 0xc000, v201
	v_add_u32_e32 v205, 0xc000, v203
	ds_read_b128 v[212:215], v204 offset:0
	ds_read_b128 v[216:219], v204 offset:2048
	ds_read_b128 v[220:223], v204 offset:4096
	ds_read_b128 v[224:227], v204 offset:6144
	ds_read_b128 v[228:231], v205 offset:0
	ds_read_b128 v[232:235], v205 offset:2048
	ds_read_b128 v[236:239], v205 offset:4096
	ds_read_b128 v[240:243], v205 offset:6144
	v_mfma_f32_16x16x32_bf16 v[2:5], v[146:149], v[130:133], v[2:5]
	v_mfma_f32_16x16x32_bf16 v[6:9], v[150:153], v[130:133], v[6:9]
	v_mfma_f32_16x16x32_bf16 v[10:13], v[154:157], v[130:133], v[10:13]
	v_mfma_f32_16x16x32_bf16 v[14:17], v[158:161], v[130:133], v[14:17]
	v_mfma_f32_16x16x32_bf16 v[18:21], v[146:149], v[134:137], v[18:21]
	v_mfma_f32_16x16x32_bf16 v[22:25], v[150:153], v[134:137], v[22:25]
	v_mfma_f32_16x16x32_bf16 v[26:29], v[154:157], v[134:137], v[26:29]
	v_mfma_f32_16x16x32_bf16 v[30:33], v[158:161], v[134:137], v[30:33]
	v_mfma_f32_16x16x32_bf16 v[34:37], v[146:149], v[138:141], v[34:37]
	v_mfma_f32_16x16x32_bf16 v[38:41], v[150:153], v[138:141], v[38:41]
	v_mfma_f32_16x16x32_bf16 v[42:45], v[154:157], v[138:141], v[42:45]
	v_mfma_f32_16x16x32_bf16 v[46:49], v[158:161], v[138:141], v[46:49]
	v_mfma_f32_16x16x32_bf16 v[50:53], v[146:149], v[142:145], v[50:53]
	v_mfma_f32_16x16x32_bf16 v[54:57], v[150:153], v[142:145], v[54:57]
	v_mfma_f32_16x16x32_bf16 v[58:61], v[154:157], v[142:145], v[58:61]
	v_mfma_f32_16x16x32_bf16 v[62:65], v[158:161], v[142:145], v[62:65]
	s_waitcnt vmcnt(6)
	s_waitcnt lgkmcnt(0)
	s_barrier
	v_add_u32_e32 v204, 0x18000, v200
	v_add_u32_e32 v205, 0x18000, v202
	ds_read_b128 v[130:133], v204 offset:0
	ds_read_b128 v[134:137], v204 offset:2048
	ds_read_b128 v[138:141], v204 offset:4096
	ds_read_b128 v[142:145], v204 offset:6144
	ds_read_b128 v[146:149], v205 offset:0
	ds_read_b128 v[150:153], v205 offset:2048
	ds_read_b128 v[154:157], v205 offset:4096
	ds_read_b128 v[158:161], v205 offset:6144
	v_mfma_f32_16x16x32_bf16 v[2:5], v[228:231], v[212:215], v[2:5]
	v_mfma_f32_16x16x32_bf16 v[6:9], v[232:235], v[212:215], v[6:9]
	s_add_u32 m0, s76, 0xc000
	s_nop 0
	global_load_lds_dwordx4 v196, s[68:69]
	v_mfma_f32_16x16x32_bf16 v[10:13], v[236:239], v[212:215], v[10:13]
	v_mfma_f32_16x16x32_bf16 v[14:17], v[240:243], v[212:215], v[14:17]
	s_add_u32 m0, s76, 0xe000
	s_nop 0
	global_load_lds_dwordx4 v197, s[68:69]
	v_mfma_f32_16x16x32_bf16 v[18:21], v[228:231], v[216:219], v[18:21]
	v_mfma_f32_16x16x32_bf16 v[22:25], v[232:235], v[216:219], v[22:25]
	s_add_u32 m0, s76, 0x10000
	s_nop 0
	global_load_lds_dwordx4 v198, s[68:69]
	v_mfma_f32_16x16x32_bf16 v[26:29], v[236:239], v[216:219], v[26:29]
	v_mfma_f32_16x16x32_bf16 v[30:33], v[240:243], v[216:219], v[30:33]
	s_add_u32 m0, s76, 0x12000
	s_nop 0
	global_load_lds_dwordx4 v199, s[68:69]
	v_mfma_f32_16x16x32_bf16 v[34:37], v[228:231], v[220:223], v[34:37]
	v_mfma_f32_16x16x32_bf16 v[38:41], v[232:235], v[220:223], v[38:41]
	s_add_u32 m0, s76, 0x14000
	s_nop 0
	global_load_lds_dwordx4 v196, s[70:71]
	v_mfma_f32_16x16x32_bf16 v[42:45], v[236:239], v[220:223], v[42:45]
	v_mfma_f32_16x16x32_bf16 v[46:49], v[240:243], v[220:223], v[46:49]
	s_add_u32 m0, s76, 0x16000
	s_nop 0
	global_load_lds_dwordx4 v197, s[70:71]
	v_mfma_f32_16x16x32_bf16 v[50:53], v[228:231], v[224:227], v[50:53]
	v_mfma_f32_16x16x32_bf16 v[54:57], v[232:235], v[224:227], v[54:57]
	s_add_u32 s68, s68, 0x80
	s_addc_u32 s69, s69, 0
	s_add_u32 s70, s70, 0x80
	s_addc_u32 s71, s71, 0
	v_mfma_f32_16x16x32_bf16 v[58:61], v[236:239], v[224:227], v[58:61]
	v_mfma_f32_16x16x32_bf16 v[62:65], v[240:243], v[224:227], v[62:65]
	s_nop 7
	v_lshlrev_b32_e32 v212, 16, v174
	v_and_b32_e32 v213, 0xffff0000, v174
	v_lshlrev_b32_e32 v214, 16, v175
	v_and_b32_e32 v215, 0xffff0000, v175
	v_pk_fma_f32 v[66:67], v[2:3], v[212:213], v[66:67]
	v_pk_fma_f32 v[68:69], v[4:5], v[214:215], v[68:69]
	v_lshlrev_b32_e32 v216, 16, v176
	v_and_b32_e32 v217, 0xffff0000, v176
	v_lshlrev_b32_e32 v218, 16, v177
	v_and_b32_e32 v219, 0xffff0000, v177
	v_pk_fma_f32 v[70:71], v[6:7], v[216:217], v[70:71]
	v_pk_fma_f32 v[72:73], v[8:9], v[218:219], v[72:73]
	v_lshlrev_b32_e32 v220, 16, v178
	v_and_b32_e32 v221, 0xffff0000, v178
	v_lshlrev_b32_e32 v222, 16, v179
	v_and_b32_e32 v223, 0xffff0000, v179
	v_pk_fma_f32 v[74:75], v[10:11], v[220:221], v[74:75]
	v_pk_fma_f32 v[76:77], v[12:13], v[222:223], v[76:77]
	v_lshlrev_b32_e32 v224, 16, v180
	v_and_b32_e32 v225, 0xffff0000, v180
	v_lshlrev_b32_e32 v226, 16, v181
	v_and_b32_e32 v227, 0xffff0000, v181
	v_pk_fma_f32 v[78:79], v[14:15], v[224:225], v[78:79]
	v_pk_fma_f32 v[80:81], v[16:17], v[226:227], v[80:81]
	v_lshlrev_b32_e32 v228, 16, v182
	v_and_b32_e32 v229, 0xffff0000, v182
	v_lshlrev_b32_e32 v230, 16, v183
	v_and_b32_e32 v231, 0xffff0000, v183
	v_pk_fma_f32 v[82:83], v[18:19], v[228:229], v[82:83]
	v_pk_fma_f32 v[84:85], v[20:21], v[230:231], v[84:85]
	v_lshlrev_b32_e32 v232, 16, v184
	v_and_b32_e32 v233, 0xffff0000, v184
	v_lshlrev_b32_e32 v234, 16, v185
	v_and_b32_e32 v235, 0xffff0000, v185
	v_pk_fma_f32 v[86:87], v[22:23], v[232:233], v[86:87]
	v_pk_fma_f32 v[88:89], v[24:25], v[234:235], v[88:89]
	v_lshlrev_b32_e32 v236, 16, v186
	v_and_b32_e32 v237, 0xffff0000, v186
	v_lshlrev_b32_e32 v238, 16, v187
	v_and_b32_e32 v239, 0xffff0000, v187
	v_pk_fma_f32 v[90:91], v[26:27], v[236:237], v[90:91]
	v_pk_fma_f32 v[92:93], v[28:29], v[238:239], v[92:93]
	v_lshlrev_b32_e32 v240, 16, v188
	v_and_b32_e32 v241, 0xffff0000, v188
	v_lshlrev_b32_e32 v242, 16, v189
	v_and_b32_e32 v243, 0xffff0000, v189
	v_pk_fma_f32 v[94:95], v[30:31], v[240:241], v[94:95]
	v_pk_fma_f32 v[96:97], v[32:33], v[242:243], v[96:97]
	v_lshlrev_b32_e32 v212, 16, v190
	v_and_b32_e32 v213, 0xffff0000, v190
	v_lshlrev_b32_e32 v214, 16, v191
	v_and_b32_e32 v215, 0xffff0000, v191
	v_pk_fma_f32 v[98:99], v[34:35], v[212:213], v[98:99]
	v_pk_fma_f32 v[100:101], v[36:37], v[214:215], v[100:101]
	v_lshlrev_b32_e32 v216, 16, v192
	v_and_b32_e32 v217, 0xffff0000, v192
	v_lshlrev_b32_e32 v218, 16, v193
	v_and_b32_e32 v219, 0xffff0000, v193
	v_pk_fma_f32 v[102:103], v[38:39], v[216:217], v[102:103]
	v_pk_fma_f32 v[104:105], v[40:41], v[218:219], v[104:105]
	v_lshlrev_b32_e32 v220, 16, v244
	v_and_b32_e32 v221, 0xffff0000, v244
	v_lshlrev_b32_e32 v222, 16, v245
	v_and_b32_e32 v223, 0xffff0000, v245
	v_pk_fma_f32 v[106:107], v[42:43], v[220:221], v[106:107]
	v_pk_fma_f32 v[108:109], v[44:45], v[222:223], v[108:109]
	v_lshlrev_b32_e32 v224, 16, v246
	v_and_b32_e32 v225, 0xffff0000, v246
	v_lshlrev_b32_e32 v226, 16, v247
	v_and_b32_e32 v227, 0xffff0000, v247
	v_pk_fma_f32 v[110:111], v[46:47], v[224:225], v[110:111]
	v_pk_fma_f32 v[112:113], v[48:49], v[226:227], v[112:113]
	v_lshlrev_b32_e32 v228, 16, v248
	v_and_b32_e32 v229, 0xffff0000, v248
	v_lshlrev_b32_e32 v230, 16, v249
	v_and_b32_e32 v231, 0xffff0000, v249
	v_pk_fma_f32 v[114:115], v[50:51], v[228:229], v[114:115]
	v_pk_fma_f32 v[116:117], v[52:53], v[230:231], v[116:117]
	v_lshlrev_b32_e32 v232, 16, v250
	v_and_b32_e32 v233, 0xffff0000, v250
	v_lshlrev_b32_e32 v234, 16, v251
	v_and_b32_e32 v235, 0xffff0000, v251
	v_pk_fma_f32 v[118:119], v[54:55], v[232:233], v[118:119]
	v_pk_fma_f32 v[120:121], v[56:57], v[234:235], v[120:121]
	v_lshlrev_b32_e32 v236, 16, v166
	v_and_b32_e32 v237, 0xffff0000, v166
	v_lshlrev_b32_e32 v238, 16, v167
	v_and_b32_e32 v239, 0xffff0000, v167
	v_pk_fma_f32 v[122:123], v[58:59], v[236:237], v[122:123]
	v_pk_fma_f32 v[124:125], v[60:61], v[238:239], v[124:125]
	v_lshlrev_b32_e32 v240, 16, v194
	v_and_b32_e32 v241, 0xffff0000, v194
	v_lshlrev_b32_e32 v242, 16, v195
	v_and_b32_e32 v243, 0xffff0000, v195
	v_pk_fma_f32 v[126:127], v[62:63], v[240:241], v[126:127]
	v_pk_fma_f32 v[128:129], v[64:65], v[242:243], v[128:129]
	s_waitcnt lgkmcnt(0)
	v_add_u32_e32 v204, 0x18000, v201
	v_add_u32_e32 v205, 0x18000, v203
	ds_read_b128 v[212:215], v204 offset:0
	ds_read_b128 v[216:219], v204 offset:2048
	ds_read_b128 v[220:223], v204 offset:4096
	ds_read_b128 v[224:227], v204 offset:6144
	ds_read_b128 v[228:231], v205 offset:0
	ds_read_b128 v[232:235], v205 offset:2048
	ds_read_b128 v[236:239], v205 offset:4096
	ds_read_b128 v[240:243], v205 offset:6144
	v_mfma_f32_16x16x32_bf16 v[2:5], v[146:149], v[130:133], 0
	v_mfma_f32_16x16x32_bf16 v[6:9], v[150:153], v[130:133], 0
	global_load_dwordx2 v[174:175], v206, s[72:73] offset:0
	v_mfma_f32_16x16x32_bf16 v[10:13], v[154:157], v[130:133], 0
	v_mfma_f32_16x16x32_bf16 v[14:17], v[158:161], v[130:133], 0
	global_load_dwordx2 v[176:177], v206, s[72:73] offset:32
	v_mfma_f32_16x16x32_bf16 v[18:21], v[146:149], v[134:137], 0
	v_mfma_f32_16x16x32_bf16 v[22:25], v[150:153], v[134:137], 0
	global_load_dwordx2 v[178:179], v206, s[72:73] offset:64
	v_mfma_f32_16x16x32_bf16 v[26:29], v[154:157], v[134:137], 0
	v_mfma_f32_16x16x32_bf16 v[30:33], v[158:161], v[134:137], 0
	global_load_dwordx2 v[180:181], v206, s[72:73] offset:96
	v_mfma_f32_16x16x32_bf16 v[34:37], v[146:149], v[138:141], 0
	v_mfma_f32_16x16x32_bf16 v[38:41], v[150:153], v[138:141], 0
	global_load_dwordx2 v[182:183], v207, s[72:73] offset:0
	v_mfma_f32_16x16x32_bf16 v[42:45], v[154:157], v[138:141], 0
	v_mfma_f32_16x16x32_bf16 v[46:49], v[158:161], v[138:141], 0
	global_load_dwordx2 v[184:185], v207, s[72:73] offset:32
	v_mfma_f32_16x16x32_bf16 v[50:53], v[146:149], v[142:145], 0
	v_mfma_f32_16x16x32_bf16 v[54:57], v[150:153], v[142:145], 0
	v_mfma_f32_16x16x32_bf16 v[58:61], v[154:157], v[142:145], 0
	v_mfma_f32_16x16x32_bf16 v[62:65], v[158:161], v[142:145], 0
	s_waitcnt vmcnt(12)
	s_waitcnt lgkmcnt(0)
	s_barrier
	v_add_u32_e32 v204, 0x0, v200
	v_add_u32_e32 v205, 0x0, v202
	ds_read_b128 v[130:133], v204 offset:0
	ds_read_b128 v[134:137], v204 offset:2048
	ds_read_b128 v[138:141], v204 offset:4096
	ds_read_b128 v[142:145], v204 offset:6144
	ds_read_b128 v[146:149], v205 offset:0
	ds_read_b128 v[150:153], v205 offset:2048
	ds_read_b128 v[154:157], v205 offset:4096
	ds_read_b128 v[158:161], v205 offset:6144
	v_mfma_f32_16x16x32_bf16 v[2:5], v[228:231], v[212:215], v[2:5]
	v_mfma_f32_16x16x32_bf16 v[6:9], v[232:235], v[212:215], v[6:9]
	s_add_u32 m0, s76, 0x18000
	s_nop 0
	global_load_lds_dwordx4 v196, s[68:69]
	v_mfma_f32_16x16x32_bf16 v[10:13], v[236:239], v[212:215], v[10:13]
	v_mfma_f32_16x16x32_bf16 v[14:17], v[240:243], v[212:215], v[14:17]
	s_add_u32 m0, s76, 0x1a000
	s_nop 0
	global_load_lds_dwordx4 v197, s[68:69]
	v_mfma_f32_16x16x32_bf16 v[18:21], v[228:231], v[216:219], v[18:21]
	v_mfma_f32_16x16x32_bf16 v[22:25], v[232:235], v[216:219], v[22:25]
	s_add_u32 m0, s76, 0x1c000
	s_nop 0
	global_load_lds_dwordx4 v198, s[68:69]
	v_mfma_f32_16x16x32_bf16 v[26:29], v[236:239], v[216:219], v[26:29]
	v_mfma_f32_16x16x32_bf16 v[30:33], v[240:243], v[216:219], v[30:33]
	s_add_u32 m0, s76, 0x1e000
	s_nop 0
	global_load_lds_dwordx4 v199, s[68:69]
	v_mfma_f32_16x16x32_bf16 v[34:37], v[228:231], v[220:223], v[34:37]
	v_mfma_f32_16x16x32_bf16 v[38:41], v[232:235], v[220:223], v[38:41]
	s_add_u32 m0, s76, 0x20000
	s_nop 0
	global_load_lds_dwordx4 v196, s[70:71]
	v_mfma_f32_16x16x32_bf16 v[42:45], v[236:239], v[220:223], v[42:45]
	v_mfma_f32_16x16x32_bf16 v[46:49], v[240:243], v[220:223], v[46:49]
	s_add_u32 m0, s76, 0x22000
	s_nop 0
	global_load_lds_dwordx4 v197, s[70:71]
	v_mfma_f32_16x16x32_bf16 v[50:53], v[228:231], v[224:227], v[50:53]
	v_mfma_f32_16x16x32_bf16 v[54:57], v[232:235], v[224:227], v[54:57]
	s_add_u32 s68, s68, 0x80
	s_addc_u32 s69, s69, 0
	s_add_u32 s70, s70, 0x80
	s_addc_u32 s71, s71, 0
	v_mfma_f32_16x16x32_bf16 v[58:61], v[236:239], v[224:227], v[58:61]
	v_mfma_f32_16x16x32_bf16 v[62:65], v[240:243], v[224:227], v[62:65]
	s_waitcnt lgkmcnt(0)
	v_add_u32_e32 v204, 0x0, v201
	v_add_u32_e32 v205, 0x0, v203
	ds_read_b128 v[212:215], v204 offset:0
	ds_read_b128 v[216:219], v204 offset:2048
	ds_read_b128 v[220:223], v204 offset:4096
	ds_read_b128 v[224:227], v204 offset:6144
	ds_read_b128 v[228:231], v205 offset:0
	ds_read_b128 v[232:235], v205 offset:2048
	ds_read_b128 v[236:239], v205 offset:4096
	ds_read_b128 v[240:243], v205 offset:6144
	v_mfma_f32_16x16x32_bf16 v[2:5], v[146:149], v[130:133], v[2:5]
	v_mfma_f32_16x16x32_bf16 v[6:9], v[150:153], v[130:133], v[6:9]
	global_load_dwordx2 v[186:187], v207, s[72:73] offset:64
	v_mfma_f32_16x16x32_bf16 v[10:13], v[154:157], v[130:133], v[10:13]
	v_mfma_f32_16x16x32_bf16 v[14:17], v[158:161], v[130:133], v[14:17]
	global_load_dwordx2 v[188:189], v207, s[72:73] offset:96
	v_mfma_f32_16x16x32_bf16 v[18:21], v[146:149], v[134:137], v[18:21]
	v_mfma_f32_16x16x32_bf16 v[22:25], v[150:153], v[134:137], v[22:25]
	global_load_dwordx2 v[190:191], v208, s[72:73] offset:0
	v_mfma_f32_16x16x32_bf16 v[26:29], v[154:157], v[134:137], v[26:29]
	v_mfma_f32_16x16x32_bf16 v[30:33], v[158:161], v[134:137], v[30:33]
	global_load_dwordx2 v[192:193], v208, s[72:73] offset:32
	v_mfma_f32_16x16x32_bf16 v[34:37], v[146:149], v[138:141], v[34:37]
	v_mfma_f32_16x16x32_bf16 v[38:41], v[150:153], v[138:141], v[38:41]
	global_load_dwordx2 v[244:245], v208, s[72:73] offset:64
	v_mfma_f32_16x16x32_bf16 v[42:45], v[154:157], v[138:141], v[42:45]
	v_mfma_f32_16x16x32_bf16 v[46:49], v[158:161], v[138:141], v[46:49]
	global_load_dwordx2 v[246:247], v208, s[72:73] offset:96
	v_mfma_f32_16x16x32_bf16 v[50:53], v[146:149], v[142:145], v[50:53]
	v_mfma_f32_16x16x32_bf16 v[54:57], v[150:153], v[142:145], v[54:57]
	v_mfma_f32_16x16x32_bf16 v[58:61], v[154:157], v[142:145], v[58:61]
	v_mfma_f32_16x16x32_bf16 v[62:65], v[158:161], v[142:145], v[62:65]
	s_waitcnt vmcnt(18)
	s_waitcnt lgkmcnt(0)
	s_barrier
	v_add_u32_e32 v204, 0xc000, v200
	v_add_u32_e32 v205, 0xc000, v202
	ds_read_b128 v[130:133], v204 offset:0
	ds_read_b128 v[134:137], v204 offset:2048
	ds_read_b128 v[138:141], v204 offset:4096
	ds_read_b128 v[142:145], v204 offset:6144
	ds_read_b128 v[146:149], v205 offset:0
	ds_read_b128 v[150:153], v205 offset:2048
	ds_read_b128 v[154:157], v205 offset:4096
	ds_read_b128 v[158:161], v205 offset:6144
	v_mfma_f32_16x16x32_bf16 v[2:5], v[228:231], v[212:215], v[2:5]
	v_mfma_f32_16x16x32_bf16 v[6:9], v[232:235], v[212:215], v[6:9]
	s_add_u32 m0, s76, 0x0
	s_nop 0
	global_load_lds_dwordx4 v196, s[68:69]
	v_mfma_f32_16x16x32_bf16 v[10:13], v[236:239], v[212:215], v[10:13]
	v_mfma_f32_16x16x32_bf16 v[14:17], v[240:243], v[212:215], v[14:17]
	s_add_u32 m0, s76, 0x2000
	s_nop 0
	global_load_lds_dwordx4 v197, s[68:69]
	v_mfma_f32_16x16x32_bf16 v[18:21], v[228:231], v[216:219], v[18:21]
	v_mfma_f32_16x16x32_bf16 v[22:25], v[232:235], v[216:219], v[22:25]
	s_add_u32 m0, s76, 0x4000
	s_nop 0
	global_load_lds_dwordx4 v198, s[68:69]
	v_mfma_f32_16x16x32_bf16 v[26:29], v[236:239], v[216:219], v[26:29]
	v_mfma_f32_16x16x32_bf16 v[30:33], v[240:243], v[216:219], v[30:33]
	s_add_u32 m0, s76, 0x6000
	s_nop 0
	global_load_lds_dwordx4 v199, s[68:69]
	v_mfma_f32_16x16x32_bf16 v[34:37], v[228:231], v[220:223], v[34:37]
	v_mfma_f32_16x16x32_bf16 v[38:41], v[232:235], v[220:223], v[38:41]
	s_add_u32 m0, s76, 0x8000
	s_nop 0
	global_load_lds_dwordx4 v196, s[70:71]
	v_mfma_f32_16x16x32_bf16 v[42:45], v[236:239], v[220:223], v[42:45]
	v_mfma_f32_16x16x32_bf16 v[46:49], v[240:243], v[220:223], v[46:49]
	s_add_u32 m0, s76, 0xa000
	s_nop 0
	global_load_lds_dwordx4 v197, s[70:71]
	v_mfma_f32_16x16x32_bf16 v[50:53], v[228:231], v[224:227], v[50:53]
	v_mfma_f32_16x16x32_bf16 v[54:57], v[232:235], v[224:227], v[54:57]
	s_add_u32 s68, s68, 0x80
	s_addc_u32 s69, s69, 0
	s_add_u32 s70, s70, 0x80
	s_addc_u32 s71, s71, 0
	v_mfma_f32_16x16x32_bf16 v[58:61], v[236:239], v[224:227], v[58:61]
	v_mfma_f32_16x16x32_bf16 v[62:65], v[240:243], v[224:227], v[62:65]
	s_waitcnt lgkmcnt(0)
	v_add_u32_e32 v204, 0xc000, v201
	v_add_u32_e32 v205, 0xc000, v203
	ds_read_b128 v[212:215], v204 offset:0
	ds_read_b128 v[216:219], v204 offset:2048
	ds_read_b128 v[220:223], v204 offset:4096
	ds_read_b128 v[224:227], v204 offset:6144
	ds_read_b128 v[228:231], v205 offset:0
	ds_read_b128 v[232:235], v205 offset:2048
	ds_read_b128 v[236:239], v205 offset:4096
	ds_read_b128 v[240:243], v205 offset:6144
	v_mfma_f32_16x16x32_bf16 v[2:5], v[146:149], v[130:133], v[2:5]
	v_mfma_f32_16x16x32_bf16 v[6:9], v[150:153], v[130:133], v[6:9]
	global_load_dwordx2 v[248:249], v209, s[72:73] offset:0
	v_mfma_f32_16x16x32_bf16 v[10:13], v[154:157], v[130:133], v[10:13]
	v_mfma_f32_16x16x32_bf16 v[14:17], v[158:161], v[130:133], v[14:17]
	global_load_dwordx2 v[250:251], v209, s[72:73] offset:32
	v_mfma_f32_16x16x32_bf16 v[18:21], v[146:149], v[134:137], v[18:21]
	v_mfma_f32_16x16x32_bf16 v[22:25], v[150:153], v[134:137], v[22:25]
	global_load_dwordx2 v[166:167], v209, s[72:73] offset:64
	v_mfma_f32_16x16x32_bf16 v[26:29], v[154:157], v[134:137], v[26:29]
	v_mfma_f32_16x16x32_bf16 v[30:33], v[158:161], v[134:137], v[30:33]
	global_load_dwordx2 v[194:195], v209, s[72:73] offset:96
	v_mfma_f32_16x16x32_bf16 v[34:37], v[146:149], v[138:141], v[34:37]
	v_mfma_f32_16x16x32_bf16 v[38:41], v[150:153], v[138:141], v[38:41]
	s_add_u32 s72, s72, 0x800
	s_addc_u32 s73, s73, 0
	v_mfma_f32_16x16x32_bf16 v[42:45], v[154:157], v[138:141], v[42:45]
	v_mfma_f32_16x16x32_bf16 v[46:49], v[158:161], v[138:141], v[46:49]
	v_mfma_f32_16x16x32_bf16 v[50:53], v[146:149], v[142:145], v[50:53]
	v_mfma_f32_16x16x32_bf16 v[54:57], v[150:153], v[142:145], v[54:57]
	v_mfma_f32_16x16x32_bf16 v[58:61], v[154:157], v[142:145], v[58:61]
	v_mfma_f32_16x16x32_bf16 v[62:65], v[158:161], v[142:145], v[62:65]
	s_waitcnt vmcnt(16)
	s_waitcnt lgkmcnt(0)
	s_barrier
	v_add_u32_e32 v204, 0x18000, v200
	v_add_u32_e32 v205, 0x18000, v202
	ds_read_b128 v[130:133], v204 offset:0
	ds_read_b128 v[134:137], v204 offset:2048
	ds_read_b128 v[138:141], v204 offset:4096
	ds_read_b128 v[142:145], v204 offset:6144
	ds_read_b128 v[146:149], v205 offset:0
	ds_read_b128 v[150:153], v205 offset:2048
	ds_read_b128 v[154:157], v205 offset:4096
	ds_read_b128 v[158:161], v205 offset:6144
	v_mfma_f32_16x16x32_bf16 v[2:5], v[228:231], v[212:215], v[2:5]
	v_mfma_f32_16x16x32_bf16 v[6:9], v[232:235], v[212:215], v[6:9]
	s_add_u32 m0, s76, 0xc000
	s_nop 0
	global_load_lds_dwordx4 v196, s[68:69]
	v_mfma_f32_16x16x32_bf16 v[10:13], v[236:239], v[212:215], v[10:13]
	v_mfma_f32_16x16x32_bf16 v[14:17], v[240:243], v[212:215], v[14:17]
	s_add_u32 m0, s76, 0xe000
	s_nop 0
	global_load_lds_dwordx4 v197, s[68:69]
	v_mfma_f32_16x16x32_bf16 v[18:21], v[228:231], v[216:219], v[18:21]
	v_mfma_f32_16x16x32_bf16 v[22:25], v[232:235], v[216:219], v[22:25]
	s_add_u32 m0, s76, 0x10000
	s_nop 0
	global_load_lds_dwordx4 v198, s[68:69]
	v_mfma_f32_16x16x32_bf16 v[26:29], v[236:239], v[216:219], v[26:29]
	v_mfma_f32_16x16x32_bf16 v[30:33], v[240:243], v[216:219], v[30:33]
	s_add_u32 m0, s76, 0x12000
	s_nop 0
	global_load_lds_dwordx4 v199, s[68:69]
	v_mfma_f32_16x16x32_bf16 v[34:37], v[228:231], v[220:223], v[34:37]
	v_mfma_f32_16x16x32_bf16 v[38:41], v[232:235], v[220:223], v[38:41]
	s_add_u32 m0, s76, 0x14000
	s_nop 0
	global_load_lds_dwordx4 v196, s[70:71]
	v_mfma_f32_16x16x32_bf16 v[42:45], v[236:239], v[220:223], v[42:45]
	v_mfma_f32_16x16x32_bf16 v[46:49], v[240:243], v[220:223], v[46:49]
	s_add_u32 m0, s76, 0x16000
	s_nop 0
	global_load_lds_dwordx4 v197, s[70:71]
	v_mfma_f32_16x16x32_bf16 v[50:53], v[228:231], v[224:227], v[50:53]
	v_mfma_f32_16x16x32_bf16 v[54:57], v[232:235], v[224:227], v[54:57]
	s_add_u32 s68, s68, 0x80
	s_addc_u32 s69, s69, 0
	s_add_u32 s70, s70, 0x80
	s_addc_u32 s71, s71, 0
	v_mfma_f32_16x16x32_bf16 v[58:61], v[236:239], v[224:227], v[58:61]
	v_mfma_f32_16x16x32_bf16 v[62:65], v[240:243], v[224:227], v[62:65]
	s_waitcnt lgkmcnt(0)
	v_add_u32_e32 v204, 0x18000, v201
	v_add_u32_e32 v205, 0x18000, v203
	ds_read_b128 v[212:215], v204 offset:0
	ds_read_b128 v[216:219], v204 offset:2048
	ds_read_b128 v[220:223], v204 offset:4096
	ds_read_b128 v[224:227], v204 offset:6144
	ds_read_b128 v[228:231], v205 offset:0
	ds_read_b128 v[232:235], v205 offset:2048
	ds_read_b128 v[236:239], v205 offset:4096
	ds_read_b128 v[240:243], v205 offset:6144
	v_mfma_f32_16x16x32_bf16 v[2:5], v[146:149], v[130:133], v[2:5]
	v_mfma_f32_16x16x32_bf16 v[6:9], v[150:153], v[130:133], v[6:9]
	v_mfma_f32_16x16x32_bf16 v[10:13], v[154:157], v[130:133], v[10:13]
	v_mfma_f32_16x16x32_bf16 v[14:17], v[158:161], v[130:133], v[14:17]
	v_mfma_f32_16x16x32_bf16 v[18:21], v[146:149], v[134:137], v[18:21]
	v_mfma_f32_16x16x32_bf16 v[22:25], v[150:153], v[134:137], v[22:25]
	v_mfma_f32_16x16x32_bf16 v[26:29], v[154:157], v[134:137], v[26:29]
	v_mfma_f32_16x16x32_bf16 v[30:33], v[158:161], v[134:137], v[30:33]
	v_mfma_f32_16x16x32_bf16 v[34:37], v[146:149], v[138:141], v[34:37]
	v_mfma_f32_16x16x32_bf16 v[38:41], v[150:153], v[138:141], v[38:41]
	v_mfma_f32_16x16x32_bf16 v[42:45], v[154:157], v[138:141], v[42:45]
	v_mfma_f32_16x16x32_bf16 v[46:49], v[158:161], v[138:141], v[46:49]
	v_mfma_f32_16x16x32_bf16 v[50:53], v[146:149], v[142:145], v[50:53]
	v_mfma_f32_16x16x32_bf16 v[54:57], v[150:153], v[142:145], v[54:57]
	v_mfma_f32_16x16x32_bf16 v[58:61], v[154:157], v[142:145], v[58:61]
	v_mfma_f32_16x16x32_bf16 v[62:65], v[158:161], v[142:145], v[62:65]
	s_waitcnt vmcnt(10)
	s_waitcnt lgkmcnt(0)
	s_barrier
	v_add_u32_e32 v204, 0x0, v200
	v_add_u32_e32 v205, 0x0, v202
	ds_read_b128 v[130:133], v204 offset:0
	ds_read_b128 v[134:137], v204 offset:2048
	ds_read_b128 v[138:141], v204 offset:4096
	ds_read_b128 v[142:145], v204 offset:6144
	ds_read_b128 v[146:149], v205 offset:0
	ds_read_b128 v[150:153], v205 offset:2048
	ds_read_b128 v[154:157], v205 offset:4096
	ds_read_b128 v[158:161], v205 offset:6144
	v_mfma_f32_16x16x32_bf16 v[2:5], v[228:231], v[212:215], v[2:5]
	v_mfma_f32_16x16x32_bf16 v[6:9], v[232:235], v[212:215], v[6:9]
	s_add_u32 m0, s76, 0x18000
	s_nop 0
	global_load_lds_dwordx4 v196, s[68:69]
	v_mfma_f32_16x16x32_bf16 v[10:13], v[236:239], v[212:215], v[10:13]
	v_mfma_f32_16x16x32_bf16 v[14:17], v[240:243], v[212:215], v[14:17]
	s_add_u32 m0, s76, 0x1a000
	s_nop 0
	global_load_lds_dwordx4 v197, s[68:69]
	v_mfma_f32_16x16x32_bf16 v[18:21], v[228:231], v[216:219], v[18:21]
	v_mfma_f32_16x16x32_bf16 v[22:25], v[232:235], v[216:219], v[22:25]
	s_add_u32 m0, s76, 0x1c000
	s_nop 0
	global_load_lds_dwordx4 v198, s[68:69]
	v_mfma_f32_16x16x32_bf16 v[26:29], v[236:239], v[216:219], v[26:29]
	v_mfma_f32_16x16x32_bf16 v[30:33], v[240:243], v[216:219], v[30:33]
	s_add_u32 m0, s76, 0x1e000
	s_nop 0
	global_load_lds_dwordx4 v199, s[68:69]
	v_mfma_f32_16x16x32_bf16 v[34:37], v[228:231], v[220:223], v[34:37]
	v_mfma_f32_16x16x32_bf16 v[38:41], v[232:235], v[220:223], v[38:41]
	s_add_u32 m0, s76, 0x20000
	s_nop 0
	global_load_lds_dwordx4 v196, s[70:71]
	v_mfma_f32_16x16x32_bf16 v[42:45], v[236:239], v[220:223], v[42:45]
	v_mfma_f32_16x16x32_bf16 v[46:49], v[240:243], v[220:223], v[46:49]
	s_add_u32 m0, s76, 0x22000
	s_nop 0
	global_load_lds_dwordx4 v197, s[70:71]
	v_mfma_f32_16x16x32_bf16 v[50:53], v[228:231], v[224:227], v[50:53]
	v_mfma_f32_16x16x32_bf16 v[54:57], v[232:235], v[224:227], v[54:57]
	s_add_u32 s68, s68, 0x80
	s_addc_u32 s69, s69, 0
	s_add_u32 s70, s70, 0x80
	s_addc_u32 s71, s71, 0
	v_mfma_f32_16x16x32_bf16 v[58:61], v[236:239], v[224:227], v[58:61]
	v_mfma_f32_16x16x32_bf16 v[62:65], v[240:243], v[224:227], v[62:65]
	s_waitcnt lgkmcnt(0)
	v_add_u32_e32 v204, 0x0, v201
	v_add_u32_e32 v205, 0x0, v203
	ds_read_b128 v[212:215], v204 offset:0
	ds_read_b128 v[216:219], v204 offset:2048
	ds_read_b128 v[220:223], v204 offset:4096
	ds_read_b128 v[224:227], v204 offset:6144
	ds_read_b128 v[228:231], v205 offset:0
	ds_read_b128 v[232:235], v205 offset:2048
	ds_read_b128 v[236:239], v205 offset:4096
	ds_read_b128 v[240:243], v205 offset:6144
	v_mfma_f32_16x16x32_bf16 v[2:5], v[146:149], v[130:133], v[2:5]
	v_mfma_f32_16x16x32_bf16 v[6:9], v[150:153], v[130:133], v[6:9]
	v_mfma_f32_16x16x32_bf16 v[10:13], v[154:157], v[130:133], v[10:13]
	v_mfma_f32_16x16x32_bf16 v[14:17], v[158:161], v[130:133], v[14:17]
	v_mfma_f32_16x16x32_bf16 v[18:21], v[146:149], v[134:137], v[18:21]
	v_mfma_f32_16x16x32_bf16 v[22:25], v[150:153], v[134:137], v[22:25]
	v_mfma_f32_16x16x32_bf16 v[26:29], v[154:157], v[134:137], v[26:29]
	v_mfma_f32_16x16x32_bf16 v[30:33], v[158:161], v[134:137], v[30:33]
	v_mfma_f32_16x16x32_bf16 v[34:37], v[146:149], v[138:141], v[34:37]
	v_mfma_f32_16x16x32_bf16 v[38:41], v[150:153], v[138:141], v[38:41]
	v_mfma_f32_16x16x32_bf16 v[42:45], v[154:157], v[138:141], v[42:45]
	v_mfma_f32_16x16x32_bf16 v[46:49], v[158:161], v[138:141], v[46:49]
	v_mfma_f32_16x16x32_bf16 v[50:53], v[146:149], v[142:145], v[50:53]
	v_mfma_f32_16x16x32_bf16 v[54:57], v[150:153], v[142:145], v[54:57]
	v_mfma_f32_16x16x32_bf16 v[58:61], v[154:157], v[142:145], v[58:61]
	v_mfma_f32_16x16x32_bf16 v[62:65], v[158:161], v[142:145], v[62:65]
	s_waitcnt vmcnt(6)
	s_waitcnt lgkmcnt(0)
	s_barrier
	v_add_u32_e32 v204, 0xc000, v200
	v_add_u32_e32 v205, 0xc000, v202
	ds_read_b128 v[130:133], v204 offset:0
	ds_read_b128 v[134:137], v204 offset:2048
	ds_read_b128 v[138:141], v204 offset:4096
	ds_read_b128 v[142:145], v204 offset:6144
	ds_read_b128 v[146:149], v205 offset:0
	ds_read_b128 v[150:153], v205 offset:2048
	ds_read_b128 v[154:157], v205 offset:4096
	ds_read_b128 v[158:161], v205 offset:6144
	v_mfma_f32_16x16x32_bf16 v[2:5], v[228:231], v[212:215], v[2:5]
	v_mfma_f32_16x16x32_bf16 v[6:9], v[232:235], v[212:215], v[6:9]
	s_add_u32 m0, s76, 0x0
	s_nop 0
	global_load_lds_dwordx4 v196, s[68:69]
	v_mfma_f32_16x16x32_bf16 v[10:13], v[236:239], v[212:215], v[10:13]
	v_mfma_f32_16x16x32_bf16 v[14:17], v[240:243], v[212:215], v[14:17]
	s_add_u32 m0, s76, 0x2000
	s_nop 0
	global_load_lds_dwordx4 v197, s[68:69]
	v_mfma_f32_16x16x32_bf16 v[18:21], v[228:231], v[216:219], v[18:21]
	v_mfma_f32_16x16x32_bf16 v[22:25], v[232:235], v[216:219], v[22:25]
	s_add_u32 m0, s76, 0x4000
	s_nop 0
	global_load_lds_dwordx4 v198, s[68:69]
	v_mfma_f32_16x16x32_bf16 v[26:29], v[236:239], v[216:219], v[26:29]
	v_mfma_f32_16x16x32_bf16 v[30:33], v[240:243], v[216:219], v[30:33]
	s_add_u32 m0, s76, 0x6000
	s_nop 0
	global_load_lds_dwordx4 v199, s[68:69]
	v_mfma_f32_16x16x32_bf16 v[34:37], v[228:231], v[220:223], v[34:37]
	v_mfma_f32_16x16x32_bf16 v[38:41], v[232:235], v[220:223], v[38:41]
	s_add_u32 m0, s76, 0x8000
	s_nop 0
	global_load_lds_dwordx4 v196, s[70:71]
	v_mfma_f32_16x16x32_bf16 v[42:45], v[236:239], v[220:223], v[42:45]
	v_mfma_f32_16x16x32_bf16 v[46:49], v[240:243], v[220:223], v[46:49]
	s_add_u32 m0, s76, 0xa000
	s_nop 0
	global_load_lds_dwordx4 v197, s[70:71]
	v_mfma_f32_16x16x32_bf16 v[50:53], v[228:231], v[224:227], v[50:53]
	v_mfma_f32_16x16x32_bf16 v[54:57], v[232:235], v[224:227], v[54:57]
	s_add_u32 s68, s68, 0x80
	s_addc_u32 s69, s69, 0
	s_add_u32 s70, s70, 0x80
	s_addc_u32 s71, s71, 0
	v_mfma_f32_16x16x32_bf16 v[58:61], v[236:239], v[224:227], v[58:61]
	v_mfma_f32_16x16x32_bf16 v[62:65], v[240:243], v[224:227], v[62:65]
	s_waitcnt lgkmcnt(0)
	v_add_u32_e32 v204, 0xc000, v201
	v_add_u32_e32 v205, 0xc000, v203
	ds_read_b128 v[212:215], v204 offset:0
	ds_read_b128 v[216:219], v204 offset:2048
	ds_read_b128 v[220:223], v204 offset:4096
	ds_read_b128 v[224:227], v204 offset:6144
	ds_read_b128 v[228:231], v205 offset:0
	ds_read_b128 v[232:235], v205 offset:2048
	ds_read_b128 v[236:239], v205 offset:4096
	ds_read_b128 v[240:243], v205 offset:6144
	v_mfma_f32_16x16x32_bf16 v[2:5], v[146:149], v[130:133], v[2:5]
	v_mfma_f32_16x16x32_bf16 v[6:9], v[150:153], v[130:133], v[6:9]
	v_mfma_f32_16x16x32_bf16 v[10:13], v[154:157], v[130:133], v[10:13]
	v_mfma_f32_16x16x32_bf16 v[14:17], v[158:161], v[130:133], v[14:17]
	v_mfma_f32_16x16x32_bf16 v[18:21], v[146:149], v[134:137], v[18:21]
	v_mfma_f32_16x16x32_bf16 v[22:25], v[150:153], v[134:137], v[22:25]
	v_mfma_f32_16x16x32_bf16 v[26:29], v[154:157], v[134:137], v[26:29]
	v_mfma_f32_16x16x32_bf16 v[30:33], v[158:161], v[134:137], v[30:33]
	v_mfma_f32_16x16x32_bf16 v[34:37], v[146:149], v[138:141], v[34:37]
	v_mfma_f32_16x16x32_bf16 v[38:41], v[150:153], v[138:141], v[38:41]
	v_mfma_f32_16x16x32_bf16 v[42:45], v[154:157], v[138:141], v[42:45]
	v_mfma_f32_16x16x32_bf16 v[46:49], v[158:161], v[138:141], v[46:49]
	v_mfma_f32_16x16x32_bf16 v[50:53], v[146:149], v[142:145], v[50:53]
	v_mfma_f32_16x16x32_bf16 v[54:57], v[150:153], v[142:145], v[54:57]
	v_mfma_f32_16x16x32_bf16 v[58:61], v[154:157], v[142:145], v[58:61]
	v_mfma_f32_16x16x32_bf16 v[62:65], v[158:161], v[142:145], v[62:65]
	s_waitcnt vmcnt(6)
	s_waitcnt lgkmcnt(0)
	s_barrier
	v_add_u32_e32 v204, 0x18000, v200
	v_add_u32_e32 v205, 0x18000, v202
	ds_read_b128 v[130:133], v204 offset:0
	ds_read_b128 v[134:137], v204 offset:2048
	ds_read_b128 v[138:141], v204 offset:4096
	ds_read_b128 v[142:145], v204 offset:6144
	ds_read_b128 v[146:149], v205 offset:0
	ds_read_b128 v[150:153], v205 offset:2048
	ds_read_b128 v[154:157], v205 offset:4096
	ds_read_b128 v[158:161], v205 offset:6144
	v_mfma_f32_16x16x32_bf16 v[2:5], v[228:231], v[212:215], v[2:5]
	v_mfma_f32_16x16x32_bf16 v[6:9], v[232:235], v[212:215], v[6:9]
	s_add_u32 m0, s76, 0xc000
	s_nop 0
	global_load_lds_dwordx4 v196, s[68:69]
	v_mfma_f32_16x16x32_bf16 v[10:13], v[236:239], v[212:215], v[10:13]
	v_mfma_f32_16x16x32_bf16 v[14:17], v[240:243], v[212:215], v[14:17]
	s_add_u32 m0, s76, 0xe000
	s_nop 0
	global_load_lds_dwordx4 v197, s[68:69]
	v_mfma_f32_16x16x32_bf16 v[18:21], v[228:231], v[216:219], v[18:21]
	v_mfma_f32_16x16x32_bf16 v[22:25], v[232:235], v[216:219], v[22:25]
	s_add_u32 m0, s76, 0x10000
	s_nop 0
	global_load_lds_dwordx4 v198, s[68:69]
	v_mfma_f32_16x16x32_bf16 v[26:29], v[236:239], v[216:219], v[26:29]
	v_mfma_f32_16x16x32_bf16 v[30:33], v[240:243], v[216:219], v[30:33]
	s_add_u32 m0, s76, 0x12000
	s_nop 0
	global_load_lds_dwordx4 v199, s[68:69]
	v_mfma_f32_16x16x32_bf16 v[34:37], v[228:231], v[220:223], v[34:37]
	v_mfma_f32_16x16x32_bf16 v[38:41], v[232:235], v[220:223], v[38:41]
	s_add_u32 m0, s76, 0x14000
	s_nop 0
	global_load_lds_dwordx4 v196, s[70:71]
	v_mfma_f32_16x16x32_bf16 v[42:45], v[236:239], v[220:223], v[42:45]
	v_mfma_f32_16x16x32_bf16 v[46:49], v[240:243], v[220:223], v[46:49]
	s_add_u32 m0, s76, 0x16000
	s_nop 0
	global_load_lds_dwordx4 v197, s[70:71]
	v_mfma_f32_16x16x32_bf16 v[50:53], v[228:231], v[224:227], v[50:53]
	v_mfma_f32_16x16x32_bf16 v[54:57], v[232:235], v[224:227], v[54:57]
	s_add_u32 s68, s68, 0x80
	s_addc_u32 s69, s69, 0
	s_add_u32 s70, s70, 0x80
	s_addc_u32 s71, s71, 0
	v_mfma_f32_16x16x32_bf16 v[58:61], v[236:239], v[224:227], v[58:61]
	v_mfma_f32_16x16x32_bf16 v[62:65], v[240:243], v[224:227], v[62:65]
	s_waitcnt lgkmcnt(0)
	v_add_u32_e32 v204, 0x18000, v201
	v_add_u32_e32 v205, 0x18000, v203
	ds_read_b128 v[212:215], v204 offset:0
	ds_read_b128 v[216:219], v204 offset:2048
	ds_read_b128 v[220:223], v204 offset:4096
	ds_read_b128 v[224:227], v204 offset:6144
	ds_read_b128 v[228:231], v205 offset:0
	ds_read_b128 v[232:235], v205 offset:2048
	ds_read_b128 v[236:239], v205 offset:4096
	ds_read_b128 v[240:243], v205 offset:6144
	v_mfma_f32_16x16x32_bf16 v[2:5], v[146:149], v[130:133], v[2:5]
	v_mfma_f32_16x16x32_bf16 v[6:9], v[150:153], v[130:133], v[6:9]
	v_mfma_f32_16x16x32_bf16 v[10:13], v[154:157], v[130:133], v[10:13]
	v_mfma_f32_16x16x32_bf16 v[14:17], v[158:161], v[130:133], v[14:17]
	v_mfma_f32_16x16x32_bf16 v[18:21], v[146:149], v[134:137], v[18:21]
	v_mfma_f32_16x16x32_bf16 v[22:25], v[150:153], v[134:137], v[22:25]
	v_mfma_f32_16x16x32_bf16 v[26:29], v[154:157], v[134:137], v[26:29]
	v_mfma_f32_16x16x32_bf16 v[30:33], v[158:161], v[134:137], v[30:33]
	v_mfma_f32_16x16x32_bf16 v[34:37], v[146:149], v[138:141], v[34:37]
	v_mfma_f32_16x16x32_bf16 v[38:41], v[150:153], v[138:141], v[38:41]
	v_mfma_f32_16x16x32_bf16 v[42:45], v[154:157], v[138:141], v[42:45]
	v_mfma_f32_16x16x32_bf16 v[46:49], v[158:161], v[138:141], v[46:49]
	v_mfma_f32_16x16x32_bf16 v[50:53], v[146:149], v[142:145], v[50:53]
	v_mfma_f32_16x16x32_bf16 v[54:57], v[150:153], v[142:145], v[54:57]
	v_mfma_f32_16x16x32_bf16 v[58:61], v[154:157], v[142:145], v[58:61]
	v_mfma_f32_16x16x32_bf16 v[62:65], v[158:161], v[142:145], v[62:65]
	s_waitcnt vmcnt(6)
	s_waitcnt lgkmcnt(0)
	s_barrier
	v_add_u32_e32 v204, 0x0, v200
	v_add_u32_e32 v205, 0x0, v202
	ds_read_b128 v[130:133], v204 offset:0
	ds_read_b128 v[134:137], v204 offset:2048
	ds_read_b128 v[138:141], v204 offset:4096
	ds_read_b128 v[142:145], v204 offset:6144
	ds_read_b128 v[146:149], v205 offset:0
	ds_read_b128 v[150:153], v205 offset:2048
	ds_read_b128 v[154:157], v205 offset:4096
	ds_read_b128 v[158:161], v205 offset:6144
	v_mfma_f32_16x16x32_bf16 v[2:5], v[228:231], v[212:215], v[2:5]
	v_mfma_f32_16x16x32_bf16 v[6:9], v[232:235], v[212:215], v[6:9]
	s_add_u32 m0, s76, 0x18000
	s_nop 0
	global_load_lds_dwordx4 v196, s[68:69]
	v_mfma_f32_16x16x32_bf16 v[10:13], v[236:239], v[212:215], v[10:13]
	v_mfma_f32_16x16x32_bf16 v[14:17], v[240:243], v[212:215], v[14:17]
	s_add_u32 m0, s76, 0x1a000
	s_nop 0
	global_load_lds_dwordx4 v197, s[68:69]
	v_mfma_f32_16x16x32_bf16 v[18:21], v[228:231], v[216:219], v[18:21]
	v_mfma_f32_16x16x32_bf16 v[22:25], v[232:235], v[216:219], v[22:25]
	s_add_u32 m0, s76, 0x1c000
	s_nop 0
	global_load_lds_dwordx4 v198, s[68:69]
	v_mfma_f32_16x16x32_bf16 v[26:29], v[236:239], v[216:219], v[26:29]
	v_mfma_f32_16x16x32_bf16 v[30:33], v[240:243], v[216:219], v[30:33]
	s_add_u32 m0, s76, 0x1e000
	s_nop 0
	global_load_lds_dwordx4 v199, s[68:69]
	v_mfma_f32_16x16x32_bf16 v[34:37], v[228:231], v[220:223], v[34:37]
	v_mfma_f32_16x16x32_bf16 v[38:41], v[232:235], v[220:223], v[38:41]
	s_add_u32 m0, s76, 0x20000
	s_nop 0
	global_load_lds_dwordx4 v196, s[70:71]
	v_mfma_f32_16x16x32_bf16 v[42:45], v[236:239], v[220:223], v[42:45]
	v_mfma_f32_16x16x32_bf16 v[46:49], v[240:243], v[220:223], v[46:49]
	s_add_u32 m0, s76, 0x22000
	s_nop 0
	global_load_lds_dwordx4 v197, s[70:71]
	v_mfma_f32_16x16x32_bf16 v[50:53], v[228:231], v[224:227], v[50:53]
	v_mfma_f32_16x16x32_bf16 v[54:57], v[232:235], v[224:227], v[54:57]
	s_add_u32 s68, s68, 0x80
	s_addc_u32 s69, s69, 0
	s_add_u32 s70, s70, 0x80
	s_addc_u32 s71, s71, 0
	v_mfma_f32_16x16x32_bf16 v[58:61], v[236:239], v[224:227], v[58:61]
	v_mfma_f32_16x16x32_bf16 v[62:65], v[240:243], v[224:227], v[62:65]
	s_waitcnt lgkmcnt(0)
	v_add_u32_e32 v204, 0x0, v201
	v_add_u32_e32 v205, 0x0, v203
	ds_read_b128 v[212:215], v204 offset:0
	ds_read_b128 v[216:219], v204 offset:2048
	ds_read_b128 v[220:223], v204 offset:4096
	ds_read_b128 v[224:227], v204 offset:6144
	ds_read_b128 v[228:231], v205 offset:0
	ds_read_b128 v[232:235], v205 offset:2048
	ds_read_b128 v[236:239], v205 offset:4096
	ds_read_b128 v[240:243], v205 offset:6144
	v_mfma_f32_16x16x32_bf16 v[2:5], v[146:149], v[130:133], v[2:5]
	v_mfma_f32_16x16x32_bf16 v[6:9], v[150:153], v[130:133], v[6:9]
	v_mfma_f32_16x16x32_bf16 v[10:13], v[154:157], v[130:133], v[10:13]
	v_mfma_f32_16x16x32_bf16 v[14:17], v[158:161], v[130:133], v[14:17]
	v_mfma_f32_16x16x32_bf16 v[18:21], v[146:149], v[134:137], v[18:21]
	v_mfma_f32_16x16x32_bf16 v[22:25], v[150:153], v[134:137], v[22:25]
	v_mfma_f32_16x16x32_bf16 v[26:29], v[154:157], v[134:137], v[26:29]
	v_mfma_f32_16x16x32_bf16 v[30:33], v[158:161], v[134:137], v[30:33]
	v_mfma_f32_16x16x32_bf16 v[34:37], v[146:149], v[138:141], v[34:37]
	v_mfma_f32_16x16x32_bf16 v[38:41], v[150:153], v[138:141], v[38:41]
	v_mfma_f32_16x16x32_bf16 v[42:45], v[154:157], v[138:141], v[42:45]
	v_mfma_f32_16x16x32_bf16 v[46:49], v[158:161], v[138:141], v[46:49]
	v_mfma_f32_16x16x32_bf16 v[50:53], v[146:149], v[142:145], v[50:53]
	v_mfma_f32_16x16x32_bf16 v[54:57], v[150:153], v[142:145], v[54:57]
	v_mfma_f32_16x16x32_bf16 v[58:61], v[154:157], v[142:145], v[58:61]
	v_mfma_f32_16x16x32_bf16 v[62:65], v[158:161], v[142:145], v[62:65]
	s_waitcnt vmcnt(6)
	s_waitcnt lgkmcnt(0)
	s_barrier
	v_add_u32_e32 v204, 0xc000, v200
	v_add_u32_e32 v205, 0xc000, v202
	ds_read_b128 v[130:133], v204 offset:0
	ds_read_b128 v[134:137], v204 offset:2048
	ds_read_b128 v[138:141], v204 offset:4096
	ds_read_b128 v[142:145], v204 offset:6144
	ds_read_b128 v[146:149], v205 offset:0
	ds_read_b128 v[150:153], v205 offset:2048
	ds_read_b128 v[154:157], v205 offset:4096
	ds_read_b128 v[158:161], v205 offset:6144
	v_mfma_f32_16x16x32_bf16 v[2:5], v[228:231], v[212:215], v[2:5]
	v_mfma_f32_16x16x32_bf16 v[6:9], v[232:235], v[212:215], v[6:9]
	s_add_u32 m0, s76, 0x0
	s_nop 0
	global_load_lds_dwordx4 v196, s[68:69]
	v_mfma_f32_16x16x32_bf16 v[10:13], v[236:239], v[212:215], v[10:13]
	v_mfma_f32_16x16x32_bf16 v[14:17], v[240:243], v[212:215], v[14:17]
	s_add_u32 m0, s76, 0x2000
	s_nop 0
	global_load_lds_dwordx4 v197, s[68:69]
	v_mfma_f32_16x16x32_bf16 v[18:21], v[228:231], v[216:219], v[18:21]
	v_mfma_f32_16x16x32_bf16 v[22:25], v[232:235], v[216:219], v[22:25]
	s_add_u32 m0, s76, 0x4000
	s_nop 0
	global_load_lds_dwordx4 v198, s[68:69]
	v_mfma_f32_16x16x32_bf16 v[26:29], v[236:239], v[216:219], v[26:29]
	v_mfma_f32_16x16x32_bf16 v[30:33], v[240:243], v[216:219], v[30:33]
	s_add_u32 m0, s76, 0x6000
	s_nop 0
	global_load_lds_dwordx4 v199, s[68:69]
	v_mfma_f32_16x16x32_bf16 v[34:37], v[228:231], v[220:223], v[34:37]
	v_mfma_f32_16x16x32_bf16 v[38:41], v[232:235], v[220:223], v[38:41]
	s_add_u32 m0, s76, 0x8000
	s_nop 0
	global_load_lds_dwordx4 v196, s[70:71]
	v_mfma_f32_16x16x32_bf16 v[42:45], v[236:239], v[220:223], v[42:45]
	v_mfma_f32_16x16x32_bf16 v[46:49], v[240:243], v[220:223], v[46:49]
	s_add_u32 m0, s76, 0xa000
	s_nop 0
	global_load_lds_dwordx4 v197, s[70:71]
	v_mfma_f32_16x16x32_bf16 v[50:53], v[228:231], v[224:227], v[50:53]
	v_mfma_f32_16x16x32_bf16 v[54:57], v[232:235], v[224:227], v[54:57]
	s_add_u32 s68, s68, 0x80
	s_addc_u32 s69, s69, 0
	s_add_u32 s70, s70, 0x80
	s_addc_u32 s71, s71, 0
	v_mfma_f32_16x16x32_bf16 v[58:61], v[236:239], v[224:227], v[58:61]
	v_mfma_f32_16x16x32_bf16 v[62:65], v[240:243], v[224:227], v[62:65]
	s_nop 7
	v_lshlrev_b32_e32 v212, 16, v174
	v_and_b32_e32 v213, 0xffff0000, v174
	v_lshlrev_b32_e32 v214, 16, v175
	v_and_b32_e32 v215, 0xffff0000, v175
	v_pk_fma_f32 v[66:67], v[2:3], v[212:213], v[66:67]
	v_pk_fma_f32 v[68:69], v[4:5], v[214:215], v[68:69]
	v_lshlrev_b32_e32 v216, 16, v176
	v_and_b32_e32 v217, 0xffff0000, v176
	v_lshlrev_b32_e32 v218, 16, v177
	v_and_b32_e32 v219, 0xffff0000, v177
	v_pk_fma_f32 v[70:71], v[6:7], v[216:217], v[70:71]
	v_pk_fma_f32 v[72:73], v[8:9], v[218:219], v[72:73]
	v_lshlrev_b32_e32 v220, 16, v178
	v_and_b32_e32 v221, 0xffff0000, v178
	v_lshlrev_b32_e32 v222, 16, v179
	v_and_b32_e32 v223, 0xffff0000, v179
	v_pk_fma_f32 v[74:75], v[10:11], v[220:221], v[74:75]
	v_pk_fma_f32 v[76:77], v[12:13], v[222:223], v[76:77]
	v_lshlrev_b32_e32 v224, 16, v180
	v_and_b32_e32 v225, 0xffff0000, v180
	v_lshlrev_b32_e32 v226, 16, v181
	v_and_b32_e32 v227, 0xffff0000, v181
	v_pk_fma_f32 v[78:79], v[14:15], v[224:225], v[78:79]
	v_pk_fma_f32 v[80:81], v[16:17], v[226:227], v[80:81]
	v_lshlrev_b32_e32 v228, 16, v182
	v_and_b32_e32 v229, 0xffff0000, v182
	v_lshlrev_b32_e32 v230, 16, v183
	v_and_b32_e32 v231, 0xffff0000, v183
	v_pk_fma_f32 v[82:83], v[18:19], v[228:229], v[82:83]
	v_pk_fma_f32 v[84:85], v[20:21], v[230:231], v[84:85]
	v_lshlrev_b32_e32 v232, 16, v184
	v_and_b32_e32 v233, 0xffff0000, v184
	v_lshlrev_b32_e32 v234, 16, v185
	v_and_b32_e32 v235, 0xffff0000, v185
	v_pk_fma_f32 v[86:87], v[22:23], v[232:233], v[86:87]
	v_pk_fma_f32 v[88:89], v[24:25], v[234:235], v[88:89]
	v_lshlrev_b32_e32 v236, 16, v186
	v_and_b32_e32 v237, 0xffff0000, v186
	v_lshlrev_b32_e32 v238, 16, v187
	v_and_b32_e32 v239, 0xffff0000, v187
	v_pk_fma_f32 v[90:91], v[26:27], v[236:237], v[90:91]
	v_pk_fma_f32 v[92:93], v[28:29], v[238:239], v[92:93]
	v_lshlrev_b32_e32 v240, 16, v188
	v_and_b32_e32 v241, 0xffff0000, v188
	v_lshlrev_b32_e32 v242, 16, v189
	v_and_b32_e32 v243, 0xffff0000, v189
	v_pk_fma_f32 v[94:95], v[30:31], v[240:241], v[94:95]
	v_pk_fma_f32 v[96:97], v[32:33], v[242:243], v[96:97]
	v_lshlrev_b32_e32 v212, 16, v190
	v_and_b32_e32 v213, 0xffff0000, v190
	v_lshlrev_b32_e32 v214, 16, v191
	v_and_b32_e32 v215, 0xffff0000, v191
	v_pk_fma_f32 v[98:99], v[34:35], v[212:213], v[98:99]
	v_pk_fma_f32 v[100:101], v[36:37], v[214:215], v[100:101]
	v_lshlrev_b32_e32 v216, 16, v192
	v_and_b32_e32 v217, 0xffff0000, v192
	v_lshlrev_b32_e32 v218, 16, v193
	v_and_b32_e32 v219, 0xffff0000, v193
	v_pk_fma_f32 v[102:103], v[38:39], v[216:217], v[102:103]
	v_pk_fma_f32 v[104:105], v[40:41], v[218:219], v[104:105]
	v_lshlrev_b32_e32 v220, 16, v244
	v_and_b32_e32 v221, 0xffff0000, v244
	v_lshlrev_b32_e32 v222, 16, v245
	v_and_b32_e32 v223, 0xffff0000, v245
	v_pk_fma_f32 v[106:107], v[42:43], v[220:221], v[106:107]
	v_pk_fma_f32 v[108:109], v[44:45], v[222:223], v[108:109]
	v_lshlrev_b32_e32 v224, 16, v246
	v_and_b32_e32 v225, 0xffff0000, v246
	v_lshlrev_b32_e32 v226, 16, v247
	v_and_b32_e32 v227, 0xffff0000, v247
	v_pk_fma_f32 v[110:111], v[46:47], v[224:225], v[110:111]
	v_pk_fma_f32 v[112:113], v[48:49], v[226:227], v[112:113]
	v_lshlrev_b32_e32 v228, 16, v248
	v_and_b32_e32 v229, 0xffff0000, v248
	v_lshlrev_b32_e32 v230, 16, v249
	v_and_b32_e32 v231, 0xffff0000, v249
	v_pk_fma_f32 v[114:115], v[50:51], v[228:229], v[114:115]
	v_pk_fma_f32 v[116:117], v[52:53], v[230:231], v[116:117]
	v_lshlrev_b32_e32 v232, 16, v250
	v_and_b32_e32 v233, 0xffff0000, v250
	v_lshlrev_b32_e32 v234, 16, v251
	v_and_b32_e32 v235, 0xffff0000, v251
	v_pk_fma_f32 v[118:119], v[54:55], v[232:233], v[118:119]
	v_pk_fma_f32 v[120:121], v[56:57], v[234:235], v[120:121]
	v_lshlrev_b32_e32 v236, 16, v166
	v_and_b32_e32 v237, 0xffff0000, v166
	v_lshlrev_b32_e32 v238, 16, v167
	v_and_b32_e32 v239, 0xffff0000, v167
	v_pk_fma_f32 v[122:123], v[58:59], v[236:237], v[122:123]
	v_pk_fma_f32 v[124:125], v[60:61], v[238:239], v[124:125]
	v_lshlrev_b32_e32 v240, 16, v194
	v_and_b32_e32 v241, 0xffff0000, v194
	v_lshlrev_b32_e32 v242, 16, v195
	v_and_b32_e32 v243, 0xffff0000, v195
	v_pk_fma_f32 v[126:127], v[62:63], v[240:241], v[126:127]
	v_pk_fma_f32 v[128:129], v[64:65], v[242:243], v[128:129]
	s_waitcnt lgkmcnt(0)
	v_add_u32_e32 v204, 0xc000, v201
	v_add_u32_e32 v205, 0xc000, v203
	ds_read_b128 v[212:215], v204 offset:0
	ds_read_b128 v[216:219], v204 offset:2048
	ds_read_b128 v[220:223], v204 offset:4096
	ds_read_b128 v[224:227], v204 offset:6144
	ds_read_b128 v[228:231], v205 offset:0
	ds_read_b128 v[232:235], v205 offset:2048
	ds_read_b128 v[236:239], v205 offset:4096
	ds_read_b128 v[240:243], v205 offset:6144
	v_mfma_f32_16x16x32_bf16 v[2:5], v[146:149], v[130:133], 0
	v_mfma_f32_16x16x32_bf16 v[6:9], v[150:153], v[130:133], 0
	global_load_dwordx2 v[174:175], v206, s[72:73] offset:0
	v_mfma_f32_16x16x32_bf16 v[10:13], v[154:157], v[130:133], 0
	v_mfma_f32_16x16x32_bf16 v[14:17], v[158:161], v[130:133], 0
	global_load_dwordx2 v[176:177], v206, s[72:73] offset:32
	v_mfma_f32_16x16x32_bf16 v[18:21], v[146:149], v[134:137], 0
	v_mfma_f32_16x16x32_bf16 v[22:25], v[150:153], v[134:137], 0
	global_load_dwordx2 v[178:179], v206, s[72:73] offset:64
	v_mfma_f32_16x16x32_bf16 v[26:29], v[154:157], v[134:137], 0
	v_mfma_f32_16x16x32_bf16 v[30:33], v[158:161], v[134:137], 0
	global_load_dwordx2 v[180:181], v206, s[72:73] offset:96
	v_mfma_f32_16x16x32_bf16 v[34:37], v[146:149], v[138:141], 0
	v_mfma_f32_16x16x32_bf16 v[38:41], v[150:153], v[138:141], 0
	global_load_dwordx2 v[182:183], v207, s[72:73] offset:0
	v_mfma_f32_16x16x32_bf16 v[42:45], v[154:157], v[138:141], 0
	v_mfma_f32_16x16x32_bf16 v[46:49], v[158:161], v[138:141], 0
	global_load_dwordx2 v[184:185], v207, s[72:73] offset:32
	v_mfma_f32_16x16x32_bf16 v[50:53], v[146:149], v[142:145], 0
	v_mfma_f32_16x16x32_bf16 v[54:57], v[150:153], v[142:145], 0
	v_mfma_f32_16x16x32_bf16 v[58:61], v[154:157], v[142:145], 0
	v_mfma_f32_16x16x32_bf16 v[62:65], v[158:161], v[142:145], 0
	s_waitcnt vmcnt(12)
	s_waitcnt lgkmcnt(0)
	s_barrier
	v_add_u32_e32 v204, 0x18000, v200
	v_add_u32_e32 v205, 0x18000, v202
	ds_read_b128 v[130:133], v204 offset:0
	ds_read_b128 v[134:137], v204 offset:2048
	ds_read_b128 v[138:141], v204 offset:4096
	ds_read_b128 v[142:145], v204 offset:6144
	ds_read_b128 v[146:149], v205 offset:0
	ds_read_b128 v[150:153], v205 offset:2048
	ds_read_b128 v[154:157], v205 offset:4096
	ds_read_b128 v[158:161], v205 offset:6144
	v_mfma_f32_16x16x32_bf16 v[2:5], v[228:231], v[212:215], v[2:5]
	v_mfma_f32_16x16x32_bf16 v[6:9], v[232:235], v[212:215], v[6:9]
	s_add_u32 m0, s76, 0xc000
	s_nop 0
	global_load_lds_dwordx4 v196, s[68:69]
	v_mfma_f32_16x16x32_bf16 v[10:13], v[236:239], v[212:215], v[10:13]
	v_mfma_f32_16x16x32_bf16 v[14:17], v[240:243], v[212:215], v[14:17]
	s_add_u32 m0, s76, 0xe000
	s_nop 0
	global_load_lds_dwordx4 v197, s[68:69]
	v_mfma_f32_16x16x32_bf16 v[18:21], v[228:231], v[216:219], v[18:21]
	v_mfma_f32_16x16x32_bf16 v[22:25], v[232:235], v[216:219], v[22:25]
	s_add_u32 m0, s76, 0x10000
	s_nop 0
	global_load_lds_dwordx4 v198, s[68:69]
	v_mfma_f32_16x16x32_bf16 v[26:29], v[236:239], v[216:219], v[26:29]
	v_mfma_f32_16x16x32_bf16 v[30:33], v[240:243], v[216:219], v[30:33]
	s_add_u32 m0, s76, 0x12000
	s_nop 0
	global_load_lds_dwordx4 v199, s[68:69]
	v_mfma_f32_16x16x32_bf16 v[34:37], v[228:231], v[220:223], v[34:37]
	v_mfma_f32_16x16x32_bf16 v[38:41], v[232:235], v[220:223], v[38:41]
	s_add_u32 m0, s76, 0x14000
	s_nop 0
	global_load_lds_dwordx4 v196, s[70:71]
	v_mfma_f32_16x16x32_bf16 v[42:45], v[236:239], v[220:223], v[42:45]
	v_mfma_f32_16x16x32_bf16 v[46:49], v[240:243], v[220:223], v[46:49]
	s_add_u32 m0, s76, 0x16000
	s_nop 0
	global_load_lds_dwordx4 v197, s[70:71]
	v_mfma_f32_16x16x32_bf16 v[50:53], v[228:231], v[224:227], v[50:53]
	v_mfma_f32_16x16x32_bf16 v[54:57], v[232:235], v[224:227], v[54:57]
	s_add_u32 s68, s68, 0x80
	s_addc_u32 s69, s69, 0
	s_add_u32 s70, s70, 0x80
	s_addc_u32 s71, s71, 0
	v_mfma_f32_16x16x32_bf16 v[58:61], v[236:239], v[224:227], v[58:61]
	v_mfma_f32_16x16x32_bf16 v[62:65], v[240:243], v[224:227], v[62:65]
	s_waitcnt lgkmcnt(0)
	v_add_u32_e32 v204, 0x18000, v201
	v_add_u32_e32 v205, 0x18000, v203
	ds_read_b128 v[212:215], v204 offset:0
	ds_read_b128 v[216:219], v204 offset:2048
	ds_read_b128 v[220:223], v204 offset:4096
	ds_read_b128 v[224:227], v204 offset:6144
	ds_read_b128 v[228:231], v205 offset:0
	ds_read_b128 v[232:235], v205 offset:2048
	ds_read_b128 v[236:239], v205 offset:4096
	ds_read_b128 v[240:243], v205 offset:6144
	v_mfma_f32_16x16x32_bf16 v[2:5], v[146:149], v[130:133], v[2:5]
	v_mfma_f32_16x16x32_bf16 v[6:9], v[150:153], v[130:133], v[6:9]
	global_load_dwordx2 v[186:187], v207, s[72:73] offset:64
	v_mfma_f32_16x16x32_bf16 v[10:13], v[154:157], v[130:133], v[10:13]
	v_mfma_f32_16x16x32_bf16 v[14:17], v[158:161], v[130:133], v[14:17]
	global_load_dwordx2 v[188:189], v207, s[72:73] offset:96
	v_mfma_f32_16x16x32_bf16 v[18:21], v[146:149], v[134:137], v[18:21]
	v_mfma_f32_16x16x32_bf16 v[22:25], v[150:153], v[134:137], v[22:25]
	global_load_dwordx2 v[190:191], v208, s[72:73] offset:0
	v_mfma_f32_16x16x32_bf16 v[26:29], v[154:157], v[134:137], v[26:29]
	v_mfma_f32_16x16x32_bf16 v[30:33], v[158:161], v[134:137], v[30:33]
	global_load_dwordx2 v[192:193], v208, s[72:73] offset:32
	v_mfma_f32_16x16x32_bf16 v[34:37], v[146:149], v[138:141], v[34:37]
	v_mfma_f32_16x16x32_bf16 v[38:41], v[150:153], v[138:141], v[38:41]
	global_load_dwordx2 v[244:245], v208, s[72:73] offset:64
	v_mfma_f32_16x16x32_bf16 v[42:45], v[154:157], v[138:141], v[42:45]
	v_mfma_f32_16x16x32_bf16 v[46:49], v[158:161], v[138:141], v[46:49]
	global_load_dwordx2 v[246:247], v208, s[72:73] offset:96
	v_mfma_f32_16x16x32_bf16 v[50:53], v[146:149], v[142:145], v[50:53]
	v_mfma_f32_16x16x32_bf16 v[54:57], v[150:153], v[142:145], v[54:57]
	v_mfma_f32_16x16x32_bf16 v[58:61], v[154:157], v[142:145], v[58:61]
	v_mfma_f32_16x16x32_bf16 v[62:65], v[158:161], v[142:145], v[62:65]
	s_waitcnt vmcnt(18)
	s_waitcnt lgkmcnt(0)
	s_barrier
	v_add_u32_e32 v204, 0x0, v200
	v_add_u32_e32 v205, 0x0, v202
	ds_read_b128 v[130:133], v204 offset:0
	ds_read_b128 v[134:137], v204 offset:2048
	ds_read_b128 v[138:141], v204 offset:4096
	ds_read_b128 v[142:145], v204 offset:6144
	ds_read_b128 v[146:149], v205 offset:0
	ds_read_b128 v[150:153], v205 offset:2048
	ds_read_b128 v[154:157], v205 offset:4096
	ds_read_b128 v[158:161], v205 offset:6144
	v_mfma_f32_16x16x32_bf16 v[2:5], v[228:231], v[212:215], v[2:5]
	v_mfma_f32_16x16x32_bf16 v[6:9], v[232:235], v[212:215], v[6:9]
	s_add_u32 m0, s76, 0x18000
	s_nop 0
	global_load_lds_dwordx4 v196, s[68:69]
	v_mfma_f32_16x16x32_bf16 v[10:13], v[236:239], v[212:215], v[10:13]
	v_mfma_f32_16x16x32_bf16 v[14:17], v[240:243], v[212:215], v[14:17]
	s_add_u32 m0, s76, 0x1a000
	s_nop 0
	global_load_lds_dwordx4 v197, s[68:69]
	v_mfma_f32_16x16x32_bf16 v[18:21], v[228:231], v[216:219], v[18:21]
	v_mfma_f32_16x16x32_bf16 v[22:25], v[232:235], v[216:219], v[22:25]
	s_add_u32 m0, s76, 0x1c000
	s_nop 0
	global_load_lds_dwordx4 v198, s[68:69]
	v_mfma_f32_16x16x32_bf16 v[26:29], v[236:239], v[216:219], v[26:29]
	v_mfma_f32_16x16x32_bf16 v[30:33], v[240:243], v[216:219], v[30:33]
	s_add_u32 m0, s76, 0x1e000
	s_nop 0
	global_load_lds_dwordx4 v199, s[68:69]
	v_mfma_f32_16x16x32_bf16 v[34:37], v[228:231], v[220:223], v[34:37]
	v_mfma_f32_16x16x32_bf16 v[38:41], v[232:235], v[220:223], v[38:41]
	s_add_u32 m0, s76, 0x20000
	s_nop 0
	global_load_lds_dwordx4 v196, s[70:71]
	v_mfma_f32_16x16x32_bf16 v[42:45], v[236:239], v[220:223], v[42:45]
	v_mfma_f32_16x16x32_bf16 v[46:49], v[240:243], v[220:223], v[46:49]
	s_add_u32 m0, s76, 0x22000
	s_nop 0
	global_load_lds_dwordx4 v197, s[70:71]
	v_mfma_f32_16x16x32_bf16 v[50:53], v[228:231], v[224:227], v[50:53]
	v_mfma_f32_16x16x32_bf16 v[54:57], v[232:235], v[224:227], v[54:57]
	s_add_u32 s68, s68, 0x80
	s_addc_u32 s69, s69, 0
	s_add_u32 s70, s70, 0x80
	s_addc_u32 s71, s71, 0
	v_mfma_f32_16x16x32_bf16 v[58:61], v[236:239], v[224:227], v[58:61]
	v_mfma_f32_16x16x32_bf16 v[62:65], v[240:243], v[224:227], v[62:65]
	s_waitcnt lgkmcnt(0)
	v_add_u32_e32 v204, 0x0, v201
	v_add_u32_e32 v205, 0x0, v203
	ds_read_b128 v[212:215], v204 offset:0
	ds_read_b128 v[216:219], v204 offset:2048
	ds_read_b128 v[220:223], v204 offset:4096
	ds_read_b128 v[224:227], v204 offset:6144
	ds_read_b128 v[228:231], v205 offset:0
	ds_read_b128 v[232:235], v205 offset:2048
	ds_read_b128 v[236:239], v205 offset:4096
	ds_read_b128 v[240:243], v205 offset:6144
	v_mfma_f32_16x16x32_bf16 v[2:5], v[146:149], v[130:133], v[2:5]
	v_mfma_f32_16x16x32_bf16 v[6:9], v[150:153], v[130:133], v[6:9]
	global_load_dwordx2 v[248:249], v209, s[72:73] offset:0
	v_mfma_f32_16x16x32_bf16 v[10:13], v[154:157], v[130:133], v[10:13]
	v_mfma_f32_16x16x32_bf16 v[14:17], v[158:161], v[130:133], v[14:17]
	global_load_dwordx2 v[250:251], v209, s[72:73] offset:32
	v_mfma_f32_16x16x32_bf16 v[18:21], v[146:149], v[134:137], v[18:21]
	v_mfma_f32_16x16x32_bf16 v[22:25], v[150:153], v[134:137], v[22:25]
	global_load_dwordx2 v[166:167], v209, s[72:73] offset:64
	v_mfma_f32_16x16x32_bf16 v[26:29], v[154:157], v[134:137], v[26:29]
	v_mfma_f32_16x16x32_bf16 v[30:33], v[158:161], v[134:137], v[30:33]
	global_load_dwordx2 v[194:195], v209, s[72:73] offset:96
	v_mfma_f32_16x16x32_bf16 v[34:37], v[146:149], v[138:141], v[34:37]
	v_mfma_f32_16x16x32_bf16 v[38:41], v[150:153], v[138:141], v[38:41]
	s_add_u32 s72, s72, 0x800
	s_addc_u32 s73, s73, 0
	v_mfma_f32_16x16x32_bf16 v[42:45], v[154:157], v[138:141], v[42:45]
	v_mfma_f32_16x16x32_bf16 v[46:49], v[158:161], v[138:141], v[46:49]
	v_mfma_f32_16x16x32_bf16 v[50:53], v[146:149], v[142:145], v[50:53]
	v_mfma_f32_16x16x32_bf16 v[54:57], v[150:153], v[142:145], v[54:57]
	v_mfma_f32_16x16x32_bf16 v[58:61], v[154:157], v[142:145], v[58:61]
	v_mfma_f32_16x16x32_bf16 v[62:65], v[158:161], v[142:145], v[62:65]
	s_waitcnt vmcnt(16)
	s_waitcnt lgkmcnt(0)
	s_barrier
	v_add_u32_e32 v204, 0xc000, v200
	v_add_u32_e32 v205, 0xc000, v202
	ds_read_b128 v[130:133], v204 offset:0
	ds_read_b128 v[134:137], v204 offset:2048
	ds_read_b128 v[138:141], v204 offset:4096
	ds_read_b128 v[142:145], v204 offset:6144
	ds_read_b128 v[146:149], v205 offset:0
	ds_read_b128 v[150:153], v205 offset:2048
	ds_read_b128 v[154:157], v205 offset:4096
	ds_read_b128 v[158:161], v205 offset:6144
	v_mfma_f32_16x16x32_bf16 v[2:5], v[228:231], v[212:215], v[2:5]
	v_mfma_f32_16x16x32_bf16 v[6:9], v[232:235], v[212:215], v[6:9]
	s_add_u32 m0, s76, 0x0
	s_nop 0
	global_load_lds_dwordx4 v196, s[68:69]
	v_mfma_f32_16x16x32_bf16 v[10:13], v[236:239], v[212:215], v[10:13]
	v_mfma_f32_16x16x32_bf16 v[14:17], v[240:243], v[212:215], v[14:17]
	s_add_u32 m0, s76, 0x2000
	s_nop 0
	global_load_lds_dwordx4 v197, s[68:69]
	v_mfma_f32_16x16x32_bf16 v[18:21], v[228:231], v[216:219], v[18:21]
	v_mfma_f32_16x16x32_bf16 v[22:25], v[232:235], v[216:219], v[22:25]
	s_add_u32 m0, s76, 0x4000
	s_nop 0
	global_load_lds_dwordx4 v198, s[68:69]
	v_mfma_f32_16x16x32_bf16 v[26:29], v[236:239], v[216:219], v[26:29]
	v_mfma_f32_16x16x32_bf16 v[30:33], v[240:243], v[216:219], v[30:33]
	s_add_u32 m0, s76, 0x6000
	s_nop 0
	global_load_lds_dwordx4 v199, s[68:69]
	v_mfma_f32_16x16x32_bf16 v[34:37], v[228:231], v[220:223], v[34:37]
	v_mfma_f32_16x16x32_bf16 v[38:41], v[232:235], v[220:223], v[38:41]
	s_add_u32 m0, s76, 0x8000
	s_nop 0
	global_load_lds_dwordx4 v196, s[70:71]
	v_mfma_f32_16x16x32_bf16 v[42:45], v[236:239], v[220:223], v[42:45]
	v_mfma_f32_16x16x32_bf16 v[46:49], v[240:243], v[220:223], v[46:49]
	s_add_u32 m0, s76, 0xa000
	s_nop 0
	global_load_lds_dwordx4 v197, s[70:71]
	v_mfma_f32_16x16x32_bf16 v[50:53], v[228:231], v[224:227], v[50:53]
	v_mfma_f32_16x16x32_bf16 v[54:57], v[232:235], v[224:227], v[54:57]
	s_add_u32 s68, s68, 0x80
	s_addc_u32 s69, s69, 0
	s_add_u32 s70, s70, 0x80
	s_addc_u32 s71, s71, 0
	v_mfma_f32_16x16x32_bf16 v[58:61], v[236:239], v[224:227], v[58:61]
	v_mfma_f32_16x16x32_bf16 v[62:65], v[240:243], v[224:227], v[62:65]
	s_waitcnt lgkmcnt(0)
	v_add_u32_e32 v204, 0xc000, v201
	v_add_u32_e32 v205, 0xc000, v203
	ds_read_b128 v[212:215], v204 offset:0
	ds_read_b128 v[216:219], v204 offset:2048
	ds_read_b128 v[220:223], v204 offset:4096
	ds_read_b128 v[224:227], v204 offset:6144
	ds_read_b128 v[228:231], v205 offset:0
	ds_read_b128 v[232:235], v205 offset:2048
	ds_read_b128 v[236:239], v205 offset:4096
	ds_read_b128 v[240:243], v205 offset:6144
	v_mfma_f32_16x16x32_bf16 v[2:5], v[146:149], v[130:133], v[2:5]
	v_mfma_f32_16x16x32_bf16 v[6:9], v[150:153], v[130:133], v[6:9]
	v_mfma_f32_16x16x32_bf16 v[10:13], v[154:157], v[130:133], v[10:13]
	v_mfma_f32_16x16x32_bf16 v[14:17], v[158:161], v[130:133], v[14:17]
	v_mfma_f32_16x16x32_bf16 v[18:21], v[146:149], v[134:137], v[18:21]
	v_mfma_f32_16x16x32_bf16 v[22:25], v[150:153], v[134:137], v[22:25]
	v_mfma_f32_16x16x32_bf16 v[26:29], v[154:157], v[134:137], v[26:29]
	v_mfma_f32_16x16x32_bf16 v[30:33], v[158:161], v[134:137], v[30:33]
	v_mfma_f32_16x16x32_bf16 v[34:37], v[146:149], v[138:141], v[34:37]
	v_mfma_f32_16x16x32_bf16 v[38:41], v[150:153], v[138:141], v[38:41]
	v_mfma_f32_16x16x32_bf16 v[42:45], v[154:157], v[138:141], v[42:45]
	v_mfma_f32_16x16x32_bf16 v[46:49], v[158:161], v[138:141], v[46:49]
	v_mfma_f32_16x16x32_bf16 v[50:53], v[146:149], v[142:145], v[50:53]
	v_mfma_f32_16x16x32_bf16 v[54:57], v[150:153], v[142:145], v[54:57]
	v_mfma_f32_16x16x32_bf16 v[58:61], v[154:157], v[142:145], v[58:61]
	v_mfma_f32_16x16x32_bf16 v[62:65], v[158:161], v[142:145], v[62:65]
	s_waitcnt vmcnt(10)
	s_waitcnt lgkmcnt(0)
	s_barrier
	v_add_u32_e32 v204, 0x18000, v200
	v_add_u32_e32 v205, 0x18000, v202
	ds_read_b128 v[130:133], v204 offset:0
	ds_read_b128 v[134:137], v204 offset:2048
	ds_read_b128 v[138:141], v204 offset:4096
	ds_read_b128 v[142:145], v204 offset:6144
	ds_read_b128 v[146:149], v205 offset:0
	ds_read_b128 v[150:153], v205 offset:2048
	ds_read_b128 v[154:157], v205 offset:4096
	ds_read_b128 v[158:161], v205 offset:6144
	v_mfma_f32_16x16x32_bf16 v[2:5], v[228:231], v[212:215], v[2:5]
	v_mfma_f32_16x16x32_bf16 v[6:9], v[232:235], v[212:215], v[6:9]
	s_add_u32 m0, s76, 0xc000
	s_nop 0
	global_load_lds_dwordx4 v196, s[68:69]
	v_mfma_f32_16x16x32_bf16 v[10:13], v[236:239], v[212:215], v[10:13]
	v_mfma_f32_16x16x32_bf16 v[14:17], v[240:243], v[212:215], v[14:17]
	s_add_u32 m0, s76, 0xe000
	s_nop 0
	global_load_lds_dwordx4 v197, s[68:69]
	v_mfma_f32_16x16x32_bf16 v[18:21], v[228:231], v[216:219], v[18:21]
	v_mfma_f32_16x16x32_bf16 v[22:25], v[232:235], v[216:219], v[22:25]
	s_add_u32 m0, s76, 0x10000
	s_nop 0
	global_load_lds_dwordx4 v198, s[68:69]
	v_mfma_f32_16x16x32_bf16 v[26:29], v[236:239], v[216:219], v[26:29]
	v_mfma_f32_16x16x32_bf16 v[30:33], v[240:243], v[216:219], v[30:33]
	s_add_u32 m0, s76, 0x12000
	s_nop 0
	global_load_lds_dwordx4 v199, s[68:69]
	v_mfma_f32_16x16x32_bf16 v[34:37], v[228:231], v[220:223], v[34:37]
	v_mfma_f32_16x16x32_bf16 v[38:41], v[232:235], v[220:223], v[38:41]
	s_add_u32 m0, s76, 0x14000
	s_nop 0
	global_load_lds_dwordx4 v196, s[70:71]
	v_mfma_f32_16x16x32_bf16 v[42:45], v[236:239], v[220:223], v[42:45]
	v_mfma_f32_16x16x32_bf16 v[46:49], v[240:243], v[220:223], v[46:49]
	s_add_u32 m0, s76, 0x16000
	s_nop 0
	global_load_lds_dwordx4 v197, s[70:71]
	v_mfma_f32_16x16x32_bf16 v[50:53], v[228:231], v[224:227], v[50:53]
	v_mfma_f32_16x16x32_bf16 v[54:57], v[232:235], v[224:227], v[54:57]
	s_add_u32 s68, s68, 0x80
	s_addc_u32 s69, s69, 0
	s_add_u32 s70, s70, 0x80
	s_addc_u32 s71, s71, 0
	v_mfma_f32_16x16x32_bf16 v[58:61], v[236:239], v[224:227], v[58:61]
	v_mfma_f32_16x16x32_bf16 v[62:65], v[240:243], v[224:227], v[62:65]
	s_waitcnt lgkmcnt(0)
	v_add_u32_e32 v204, 0x18000, v201
	v_add_u32_e32 v205, 0x18000, v203
	ds_read_b128 v[212:215], v204 offset:0
	ds_read_b128 v[216:219], v204 offset:2048
	ds_read_b128 v[220:223], v204 offset:4096
	ds_read_b128 v[224:227], v204 offset:6144
	ds_read_b128 v[228:231], v205 offset:0
	ds_read_b128 v[232:235], v205 offset:2048
	ds_read_b128 v[236:239], v205 offset:4096
	ds_read_b128 v[240:243], v205 offset:6144
	v_mfma_f32_16x16x32_bf16 v[2:5], v[146:149], v[130:133], v[2:5]
	v_mfma_f32_16x16x32_bf16 v[6:9], v[150:153], v[130:133], v[6:9]
	v_mfma_f32_16x16x32_bf16 v[10:13], v[154:157], v[130:133], v[10:13]
	v_mfma_f32_16x16x32_bf16 v[14:17], v[158:161], v[130:133], v[14:17]
	v_mfma_f32_16x16x32_bf16 v[18:21], v[146:149], v[134:137], v[18:21]
	v_mfma_f32_16x16x32_bf16 v[22:25], v[150:153], v[134:137], v[22:25]
	v_mfma_f32_16x16x32_bf16 v[26:29], v[154:157], v[134:137], v[26:29]
	v_mfma_f32_16x16x32_bf16 v[30:33], v[158:161], v[134:137], v[30:33]
	v_mfma_f32_16x16x32_bf16 v[34:37], v[146:149], v[138:141], v[34:37]
	v_mfma_f32_16x16x32_bf16 v[38:41], v[150:153], v[138:141], v[38:41]
	v_mfma_f32_16x16x32_bf16 v[42:45], v[154:157], v[138:141], v[42:45]
	v_mfma_f32_16x16x32_bf16 v[46:49], v[158:161], v[138:141], v[46:49]
	v_mfma_f32_16x16x32_bf16 v[50:53], v[146:149], v[142:145], v[50:53]
	v_mfma_f32_16x16x32_bf16 v[54:57], v[150:153], v[142:145], v[54:57]
	v_mfma_f32_16x16x32_bf16 v[58:61], v[154:157], v[142:145], v[58:61]
	v_mfma_f32_16x16x32_bf16 v[62:65], v[158:161], v[142:145], v[62:65]
	s_waitcnt vmcnt(6)
	s_waitcnt lgkmcnt(0)
	s_barrier
	v_add_u32_e32 v204, 0x0, v200
	v_add_u32_e32 v205, 0x0, v202
	ds_read_b128 v[130:133], v204 offset:0
	ds_read_b128 v[134:137], v204 offset:2048
	ds_read_b128 v[138:141], v204 offset:4096
	ds_read_b128 v[142:145], v204 offset:6144
	ds_read_b128 v[146:149], v205 offset:0
	ds_read_b128 v[150:153], v205 offset:2048
	ds_read_b128 v[154:157], v205 offset:4096
	ds_read_b128 v[158:161], v205 offset:6144
	v_mfma_f32_16x16x32_bf16 v[2:5], v[228:231], v[212:215], v[2:5]
	v_mfma_f32_16x16x32_bf16 v[6:9], v[232:235], v[212:215], v[6:9]
	s_add_u32 m0, s76, 0x18000
	s_nop 0
	global_load_lds_dwordx4 v196, s[68:69]
	v_mfma_f32_16x16x32_bf16 v[10:13], v[236:239], v[212:215], v[10:13]
	v_mfma_f32_16x16x32_bf16 v[14:17], v[240:243], v[212:215], v[14:17]
	s_add_u32 m0, s76, 0x1a000
	s_nop 0
	global_load_lds_dwordx4 v197, s[68:69]
	v_mfma_f32_16x16x32_bf16 v[18:21], v[228:231], v[216:219], v[18:21]
	v_mfma_f32_16x16x32_bf16 v[22:25], v[232:235], v[216:219], v[22:25]
	s_add_u32 m0, s76, 0x1c000
	s_nop 0
	global_load_lds_dwordx4 v198, s[68:69]
	v_mfma_f32_16x16x32_bf16 v[26:29], v[236:239], v[216:219], v[26:29]
	v_mfma_f32_16x16x32_bf16 v[30:33], v[240:243], v[216:219], v[30:33]
	s_add_u32 m0, s76, 0x1e000
	s_nop 0
	global_load_lds_dwordx4 v199, s[68:69]
	v_mfma_f32_16x16x32_bf16 v[34:37], v[228:231], v[220:223], v[34:37]
	v_mfma_f32_16x16x32_bf16 v[38:41], v[232:235], v[220:223], v[38:41]
	s_add_u32 m0, s76, 0x20000
	s_nop 0
	global_load_lds_dwordx4 v196, s[70:71]
	v_mfma_f32_16x16x32_bf16 v[42:45], v[236:239], v[220:223], v[42:45]
	v_mfma_f32_16x16x32_bf16 v[46:49], v[240:243], v[220:223], v[46:49]
	s_add_u32 m0, s76, 0x22000
	s_nop 0
	global_load_lds_dwordx4 v197, s[70:71]
	v_mfma_f32_16x16x32_bf16 v[50:53], v[228:231], v[224:227], v[50:53]
	v_mfma_f32_16x16x32_bf16 v[54:57], v[232:235], v[224:227], v[54:57]
	s_add_u32 s68, s68, 0x80
	s_addc_u32 s69, s69, 0
	s_add_u32 s70, s70, 0x80
	s_addc_u32 s71, s71, 0
	v_mfma_f32_16x16x32_bf16 v[58:61], v[236:239], v[224:227], v[58:61]
	v_mfma_f32_16x16x32_bf16 v[62:65], v[240:243], v[224:227], v[62:65]
	s_waitcnt lgkmcnt(0)
	v_add_u32_e32 v204, 0x0, v201
	v_add_u32_e32 v205, 0x0, v203
	ds_read_b128 v[212:215], v204 offset:0
	ds_read_b128 v[216:219], v204 offset:2048
	ds_read_b128 v[220:223], v204 offset:4096
	ds_read_b128 v[224:227], v204 offset:6144
	ds_read_b128 v[228:231], v205 offset:0
	ds_read_b128 v[232:235], v205 offset:2048
	ds_read_b128 v[236:239], v205 offset:4096
	ds_read_b128 v[240:243], v205 offset:6144
	v_mfma_f32_16x16x32_bf16 v[2:5], v[146:149], v[130:133], v[2:5]
	v_mfma_f32_16x16x32_bf16 v[6:9], v[150:153], v[130:133], v[6:9]
	v_mfma_f32_16x16x32_bf16 v[10:13], v[154:157], v[130:133], v[10:13]
	v_mfma_f32_16x16x32_bf16 v[14:17], v[158:161], v[130:133], v[14:17]
	v_mfma_f32_16x16x32_bf16 v[18:21], v[146:149], v[134:137], v[18:21]
	v_mfma_f32_16x16x32_bf16 v[22:25], v[150:153], v[134:137], v[22:25]
	v_mfma_f32_16x16x32_bf16 v[26:29], v[154:157], v[134:137], v[26:29]
	v_mfma_f32_16x16x32_bf16 v[30:33], v[158:161], v[134:137], v[30:33]
	v_mfma_f32_16x16x32_bf16 v[34:37], v[146:149], v[138:141], v[34:37]
	v_mfma_f32_16x16x32_bf16 v[38:41], v[150:153], v[138:141], v[38:41]
	v_mfma_f32_16x16x32_bf16 v[42:45], v[154:157], v[138:141], v[42:45]
	v_mfma_f32_16x16x32_bf16 v[46:49], v[158:161], v[138:141], v[46:49]
	v_mfma_f32_16x16x32_bf16 v[50:53], v[146:149], v[142:145], v[50:53]
	v_mfma_f32_16x16x32_bf16 v[54:57], v[150:153], v[142:145], v[54:57]
	v_mfma_f32_16x16x32_bf16 v[58:61], v[154:157], v[142:145], v[58:61]
	v_mfma_f32_16x16x32_bf16 v[62:65], v[158:161], v[142:145], v[62:65]
	s_waitcnt vmcnt(6)
	s_waitcnt lgkmcnt(0)
	s_barrier
	v_add_u32_e32 v204, 0xc000, v200
	v_add_u32_e32 v205, 0xc000, v202
	ds_read_b128 v[130:133], v204 offset:0
	ds_read_b128 v[134:137], v204 offset:2048
	ds_read_b128 v[138:141], v204 offset:4096
	ds_read_b128 v[142:145], v204 offset:6144
	ds_read_b128 v[146:149], v205 offset:0
	ds_read_b128 v[150:153], v205 offset:2048
	ds_read_b128 v[154:157], v205 offset:4096
	ds_read_b128 v[158:161], v205 offset:6144
	v_mfma_f32_16x16x32_bf16 v[2:5], v[228:231], v[212:215], v[2:5]
	v_mfma_f32_16x16x32_bf16 v[6:9], v[232:235], v[212:215], v[6:9]
	v_mfma_f32_16x16x32_bf16 v[10:13], v[236:239], v[212:215], v[10:13]
	v_mfma_f32_16x16x32_bf16 v[14:17], v[240:243], v[212:215], v[14:17]
	v_mfma_f32_16x16x32_bf16 v[18:21], v[228:231], v[216:219], v[18:21]
	v_mfma_f32_16x16x32_bf16 v[22:25], v[232:235], v[216:219], v[22:25]
	v_mfma_f32_16x16x32_bf16 v[26:29], v[236:239], v[216:219], v[26:29]
	v_mfma_f32_16x16x32_bf16 v[30:33], v[240:243], v[216:219], v[30:33]
	v_mfma_f32_16x16x32_bf16 v[34:37], v[228:231], v[220:223], v[34:37]
	v_mfma_f32_16x16x32_bf16 v[38:41], v[232:235], v[220:223], v[38:41]
	v_mfma_f32_16x16x32_bf16 v[42:45], v[236:239], v[220:223], v[42:45]
	v_mfma_f32_16x16x32_bf16 v[46:49], v[240:243], v[220:223], v[46:49]
	v_mfma_f32_16x16x32_bf16 v[50:53], v[228:231], v[224:227], v[50:53]
	v_mfma_f32_16x16x32_bf16 v[54:57], v[232:235], v[224:227], v[54:57]
	v_mfma_f32_16x16x32_bf16 v[58:61], v[236:239], v[224:227], v[58:61]
	v_mfma_f32_16x16x32_bf16 v[62:65], v[240:243], v[224:227], v[62:65]
	s_waitcnt lgkmcnt(0)
	v_add_u32_e32 v204, 0xc000, v201
	v_add_u32_e32 v205, 0xc000, v203
	ds_read_b128 v[212:215], v204 offset:0
	ds_read_b128 v[216:219], v204 offset:2048
	ds_read_b128 v[220:223], v204 offset:4096
	ds_read_b128 v[224:227], v204 offset:6144
	ds_read_b128 v[228:231], v205 offset:0
	ds_read_b128 v[232:235], v205 offset:2048
	ds_read_b128 v[236:239], v205 offset:4096
	ds_read_b128 v[240:243], v205 offset:6144
	v_mfma_f32_16x16x32_bf16 v[2:5], v[146:149], v[130:133], v[2:5]
	v_mfma_f32_16x16x32_bf16 v[6:9], v[150:153], v[130:133], v[6:9]
	v_mfma_f32_16x16x32_bf16 v[10:13], v[154:157], v[130:133], v[10:13]
	v_mfma_f32_16x16x32_bf16 v[14:17], v[158:161], v[130:133], v[14:17]
	v_mfma_f32_16x16x32_bf16 v[18:21], v[146:149], v[134:137], v[18:21]
	v_mfma_f32_16x16x32_bf16 v[22:25], v[150:153], v[134:137], v[22:25]
	v_mfma_f32_16x16x32_bf16 v[26:29], v[154:157], v[134:137], v[26:29]
	v_mfma_f32_16x16x32_bf16 v[30:33], v[158:161], v[134:137], v[30:33]
	v_mfma_f32_16x16x32_bf16 v[34:37], v[146:149], v[138:141], v[34:37]
	v_mfma_f32_16x16x32_bf16 v[38:41], v[150:153], v[138:141], v[38:41]
	v_mfma_f32_16x16x32_bf16 v[42:45], v[154:157], v[138:141], v[42:45]
	v_mfma_f32_16x16x32_bf16 v[46:49], v[158:161], v[138:141], v[46:49]
	v_mfma_f32_16x16x32_bf16 v[50:53], v[146:149], v[142:145], v[50:53]
	v_mfma_f32_16x16x32_bf16 v[54:57], v[150:153], v[142:145], v[54:57]
	v_mfma_f32_16x16x32_bf16 v[58:61], v[154:157], v[142:145], v[58:61]
	v_mfma_f32_16x16x32_bf16 v[62:65], v[158:161], v[142:145], v[62:65]
	s_waitcnt vmcnt(0)
	s_waitcnt lgkmcnt(0)
	s_barrier
	v_add_u32_e32 v204, 0x18000, v200
	v_add_u32_e32 v205, 0x18000, v202
	ds_read_b128 v[130:133], v204 offset:0
	ds_read_b128 v[134:137], v204 offset:2048
	ds_read_b128 v[138:141], v204 offset:4096
	ds_read_b128 v[142:145], v204 offset:6144
	ds_read_b128 v[146:149], v205 offset:0
	ds_read_b128 v[150:153], v205 offset:2048
	ds_read_b128 v[154:157], v205 offset:4096
	ds_read_b128 v[158:161], v205 offset:6144
	v_mfma_f32_16x16x32_bf16 v[2:5], v[228:231], v[212:215], v[2:5]
	v_mfma_f32_16x16x32_bf16 v[6:9], v[232:235], v[212:215], v[6:9]
	v_mfma_f32_16x16x32_bf16 v[10:13], v[236:239], v[212:215], v[10:13]
	v_mfma_f32_16x16x32_bf16 v[14:17], v[240:243], v[212:215], v[14:17]
	v_mfma_f32_16x16x32_bf16 v[18:21], v[228:231], v[216:219], v[18:21]
	v_mfma_f32_16x16x32_bf16 v[22:25], v[232:235], v[216:219], v[22:25]
	v_mfma_f32_16x16x32_bf16 v[26:29], v[236:239], v[216:219], v[26:29]
	v_mfma_f32_16x16x32_bf16 v[30:33], v[240:243], v[216:219], v[30:33]
	v_mfma_f32_16x16x32_bf16 v[34:37], v[228:231], v[220:223], v[34:37]
	v_mfma_f32_16x16x32_bf16 v[38:41], v[232:235], v[220:223], v[38:41]
	v_mfma_f32_16x16x32_bf16 v[42:45], v[236:239], v[220:223], v[42:45]
	v_mfma_f32_16x16x32_bf16 v[46:49], v[240:243], v[220:223], v[46:49]
	v_mfma_f32_16x16x32_bf16 v[50:53], v[228:231], v[224:227], v[50:53]
	v_mfma_f32_16x16x32_bf16 v[54:57], v[232:235], v[224:227], v[54:57]
	v_mfma_f32_16x16x32_bf16 v[58:61], v[236:239], v[224:227], v[58:61]
	v_mfma_f32_16x16x32_bf16 v[62:65], v[240:243], v[224:227], v[62:65]
	s_waitcnt lgkmcnt(0)
	v_add_u32_e32 v204, 0x18000, v201
	v_add_u32_e32 v205, 0x18000, v203
	ds_read_b128 v[212:215], v204 offset:0
	ds_read_b128 v[216:219], v204 offset:2048
	ds_read_b128 v[220:223], v204 offset:4096
	ds_read_b128 v[224:227], v204 offset:6144
	ds_read_b128 v[228:231], v205 offset:0
	ds_read_b128 v[232:235], v205 offset:2048
	ds_read_b128 v[236:239], v205 offset:4096
	ds_read_b128 v[240:243], v205 offset:6144
	v_mfma_f32_16x16x32_bf16 v[2:5], v[146:149], v[130:133], v[2:5]
	v_mfma_f32_16x16x32_bf16 v[6:9], v[150:153], v[130:133], v[6:9]
	v_mfma_f32_16x16x32_bf16 v[10:13], v[154:157], v[130:133], v[10:13]
	v_mfma_f32_16x16x32_bf16 v[14:17], v[158:161], v[130:133], v[14:17]
	v_mfma_f32_16x16x32_bf16 v[18:21], v[146:149], v[134:137], v[18:21]
	v_mfma_f32_16x16x32_bf16 v[22:25], v[150:153], v[134:137], v[22:25]
	v_mfma_f32_16x16x32_bf16 v[26:29], v[154:157], v[134:137], v[26:29]
	v_mfma_f32_16x16x32_bf16 v[30:33], v[158:161], v[134:137], v[30:33]
	v_mfma_f32_16x16x32_bf16 v[34:37], v[146:149], v[138:141], v[34:37]
	v_mfma_f32_16x16x32_bf16 v[38:41], v[150:153], v[138:141], v[38:41]
	v_mfma_f32_16x16x32_bf16 v[42:45], v[154:157], v[138:141], v[42:45]
	v_mfma_f32_16x16x32_bf16 v[46:49], v[158:161], v[138:141], v[46:49]
	v_mfma_f32_16x16x32_bf16 v[50:53], v[146:149], v[142:145], v[50:53]
	v_mfma_f32_16x16x32_bf16 v[54:57], v[150:153], v[142:145], v[54:57]
	v_mfma_f32_16x16x32_bf16 v[58:61], v[154:157], v[142:145], v[58:61]
	v_mfma_f32_16x16x32_bf16 v[62:65], v[158:161], v[142:145], v[62:65]
	s_waitcnt lgkmcnt(0)
	v_mfma_f32_16x16x32_bf16 v[2:5], v[228:231], v[212:215], v[2:5]
	v_mfma_f32_16x16x32_bf16 v[6:9], v[232:235], v[212:215], v[6:9]
	v_mfma_f32_16x16x32_bf16 v[10:13], v[236:239], v[212:215], v[10:13]
	v_mfma_f32_16x16x32_bf16 v[14:17], v[240:243], v[212:215], v[14:17]
	v_mfma_f32_16x16x32_bf16 v[18:21], v[228:231], v[216:219], v[18:21]
	v_mfma_f32_16x16x32_bf16 v[22:25], v[232:235], v[216:219], v[22:25]
	v_mfma_f32_16x16x32_bf16 v[26:29], v[236:239], v[216:219], v[26:29]
	v_mfma_f32_16x16x32_bf16 v[30:33], v[240:243], v[216:219], v[30:33]
	v_mfma_f32_16x16x32_bf16 v[34:37], v[228:231], v[220:223], v[34:37]
	v_mfma_f32_16x16x32_bf16 v[38:41], v[232:235], v[220:223], v[38:41]
	v_mfma_f32_16x16x32_bf16 v[42:45], v[236:239], v[220:223], v[42:45]
	v_mfma_f32_16x16x32_bf16 v[46:49], v[240:243], v[220:223], v[46:49]
	v_mfma_f32_16x16x32_bf16 v[50:53], v[228:231], v[224:227], v[50:53]
	v_mfma_f32_16x16x32_bf16 v[54:57], v[232:235], v[224:227], v[54:57]
	v_mfma_f32_16x16x32_bf16 v[58:61], v[236:239], v[224:227], v[58:61]
	v_mfma_f32_16x16x32_bf16 v[62:65], v[240:243], v[224:227], v[62:65]
	s_nop 7
	v_lshlrev_b32_e32 v212, 16, v174
	v_and_b32_e32 v213, 0xffff0000, v174
	v_lshlrev_b32_e32 v214, 16, v175
	v_and_b32_e32 v215, 0xffff0000, v175
	v_pk_fma_f32 v[66:67], v[2:3], v[212:213], v[66:67]
	v_pk_fma_f32 v[68:69], v[4:5], v[214:215], v[68:69]
	s_nop 0
	v_cvt_pk_bf16_f32 v66, v66, v67
	v_cvt_pk_bf16_f32 v67, v68, v69
	global_store_dwordx2 v210, v[66:67], s[74:75] offset:0
	v_lshlrev_b32_e32 v216, 16, v176
	v_and_b32_e32 v217, 0xffff0000, v176
	v_lshlrev_b32_e32 v218, 16, v177
	v_and_b32_e32 v219, 0xffff0000, v177
	v_pk_fma_f32 v[70:71], v[6:7], v[216:217], v[70:71]
	v_pk_fma_f32 v[72:73], v[8:9], v[218:219], v[72:73]
	s_nop 0
	v_cvt_pk_bf16_f32 v70, v70, v71
	v_cvt_pk_bf16_f32 v71, v72, v73
	global_store_dwordx2 v210, v[70:71], s[74:75] offset:32
	v_lshlrev_b32_e32 v220, 16, v178
	v_and_b32_e32 v221, 0xffff0000, v178
	v_lshlrev_b32_e32 v222, 16, v179
	v_and_b32_e32 v223, 0xffff0000, v179
	v_pk_fma_f32 v[74:75], v[10:11], v[220:221], v[74:75]
	v_pk_fma_f32 v[76:77], v[12:13], v[222:223], v[76:77]
	s_nop 0
	v_cvt_pk_bf16_f32 v74, v74, v75
	v_cvt_pk_bf16_f32 v75, v76, v77
	global_store_dwordx2 v210, v[74:75], s[74:75] offset:64
	v_lshlrev_b32_e32 v224, 16, v180
	v_and_b32_e32 v225, 0xffff0000, v180
	v_lshlrev_b32_e32 v226, 16, v181
	v_and_b32_e32 v227, 0xffff0000, v181
	v_pk_fma_f32 v[78:79], v[14:15], v[224:225], v[78:79]
	v_pk_fma_f32 v[80:81], v[16:17], v[226:227], v[80:81]
	s_nop 0
	v_cvt_pk_bf16_f32 v78, v78, v79
	v_cvt_pk_bf16_f32 v79, v80, v81
	global_store_dwordx2 v210, v[78:79], s[74:75] offset:96
	v_lshlrev_b32_e32 v228, 16, v182
	v_and_b32_e32 v229, 0xffff0000, v182
	v_lshlrev_b32_e32 v230, 16, v183
	v_and_b32_e32 v231, 0xffff0000, v183
	v_pk_fma_f32 v[82:83], v[18:19], v[228:229], v[82:83]
	v_pk_fma_f32 v[84:85], v[20:21], v[230:231], v[84:85]
	s_nop 0
	v_cvt_pk_bf16_f32 v82, v82, v83
	v_cvt_pk_bf16_f32 v83, v84, v85
	global_store_dwordx2 v211, v[82:83], s[74:75] offset:0
	v_lshlrev_b32_e32 v232, 16, v184
	v_and_b32_e32 v233, 0xffff0000, v184
	v_lshlrev_b32_e32 v234, 16, v185
	v_and_b32_e32 v235, 0xffff0000, v185
	v_pk_fma_f32 v[86:87], v[22:23], v[232:233], v[86:87]
	v_pk_fma_f32 v[88:89], v[24:25], v[234:235], v[88:89]
	s_nop 0
	v_cvt_pk_bf16_f32 v86, v86, v87
	v_cvt_pk_bf16_f32 v87, v88, v89
	global_store_dwordx2 v211, v[86:87], s[74:75] offset:32
	v_lshlrev_b32_e32 v236, 16, v186
	v_and_b32_e32 v237, 0xffff0000, v186
	v_lshlrev_b32_e32 v238, 16, v187
	v_and_b32_e32 v239, 0xffff0000, v187
	v_pk_fma_f32 v[90:91], v[26:27], v[236:237], v[90:91]
	v_pk_fma_f32 v[92:93], v[28:29], v[238:239], v[92:93]
	s_nop 0
	v_cvt_pk_bf16_f32 v90, v90, v91
	v_cvt_pk_bf16_f32 v91, v92, v93
	global_store_dwordx2 v211, v[90:91], s[74:75] offset:64
	v_lshlrev_b32_e32 v240, 16, v188
	v_and_b32_e32 v241, 0xffff0000, v188
	v_lshlrev_b32_e32 v242, 16, v189
	v_and_b32_e32 v243, 0xffff0000, v189
	v_pk_fma_f32 v[94:95], v[30:31], v[240:241], v[94:95]
	v_pk_fma_f32 v[96:97], v[32:33], v[242:243], v[96:97]
	s_nop 0
	v_cvt_pk_bf16_f32 v94, v94, v95
	v_cvt_pk_bf16_f32 v95, v96, v97
	global_store_dwordx2 v211, v[94:95], s[74:75] offset:96
	v_lshlrev_b32_e32 v212, 16, v190
	v_and_b32_e32 v213, 0xffff0000, v190
	v_lshlrev_b32_e32 v214, 16, v191
	v_and_b32_e32 v215, 0xffff0000, v191
	v_pk_fma_f32 v[98:99], v[34:35], v[212:213], v[98:99]
	v_pk_fma_f32 v[100:101], v[36:37], v[214:215], v[100:101]
	s_nop 0
	v_cvt_pk_bf16_f32 v98, v98, v99
	v_cvt_pk_bf16_f32 v99, v100, v101
	global_store_dwordx2 v168, v[98:99], s[74:75] offset:0
	v_lshlrev_b32_e32 v216, 16, v192
	v_and_b32_e32 v217, 0xffff0000, v192
	v_lshlrev_b32_e32 v218, 16, v193
	v_and_b32_e32 v219, 0xffff0000, v193
	v_pk_fma_f32 v[102:103], v[38:39], v[216:217], v[102:103]
	v_pk_fma_f32 v[104:105], v[40:41], v[218:219], v[104:105]
	s_nop 0
	v_cvt_pk_bf16_f32 v102, v102, v103
	v_cvt_pk_bf16_f32 v103, v104, v105
	global_store_dwordx2 v168, v[102:103], s[74:75] offset:32
	v_lshlrev_b32_e32 v220, 16, v244
	v_and_b32_e32 v221, 0xffff0000, v244
	v_lshlrev_b32_e32 v222, 16, v245
	v_and_b32_e32 v223, 0xffff0000, v245
	v_pk_fma_f32 v[106:107], v[42:43], v[220:221], v[106:107]
	v_pk_fma_f32 v[108:109], v[44:45], v[222:223], v[108:109]
	s_nop 0
	v_cvt_pk_bf16_f32 v106, v106, v107
	v_cvt_pk_bf16_f32 v107, v108, v109
	global_store_dwordx2 v168, v[106:107], s[74:75] offset:64
	v_lshlrev_b32_e32 v224, 16, v246
	v_and_b32_e32 v225, 0xffff0000, v246
	v_lshlrev_b32_e32 v226, 16, v247
	v_and_b32_e32 v227, 0xffff0000, v247
	v_pk_fma_f32 v[110:111], v[46:47], v[224:225], v[110:111]
	v_pk_fma_f32 v[112:113], v[48:49], v[226:227], v[112:113]
	s_nop 0
	v_cvt_pk_bf16_f32 v110, v110, v111
	v_cvt_pk_bf16_f32 v111, v112, v113
	global_store_dwordx2 v168, v[110:111], s[74:75] offset:96
	v_lshlrev_b32_e32 v228, 16, v248
	v_and_b32_e32 v229, 0xffff0000, v248
	v_lshlrev_b32_e32 v230, 16, v249
	v_and_b32_e32 v231, 0xffff0000, v249
	v_pk_fma_f32 v[114:115], v[50:51], v[228:229], v[114:115]
	v_pk_fma_f32 v[116:117], v[52:53], v[230:231], v[116:117]
	s_nop 0
	v_cvt_pk_bf16_f32 v114, v114, v115
	v_cvt_pk_bf16_f32 v115, v116, v117
	global_store_dwordx2 v169, v[114:115], s[74:75] offset:0
	v_lshlrev_b32_e32 v232, 16, v250
	v_and_b32_e32 v233, 0xffff0000, v250
	v_lshlrev_b32_e32 v234, 16, v251
	v_and_b32_e32 v235, 0xffff0000, v251
	v_pk_fma_f32 v[118:119], v[54:55], v[232:233], v[118:119]
	v_pk_fma_f32 v[120:121], v[56:57], v[234:235], v[120:121]
	s_nop 0
	v_cvt_pk_bf16_f32 v118, v118, v119
	v_cvt_pk_bf16_f32 v119, v120, v121
	global_store_dwordx2 v169, v[118:119], s[74:75] offset:32
	v_lshlrev_b32_e32 v236, 16, v166
	v_and_b32_e32 v237, 0xffff0000, v166
	v_lshlrev_b32_e32 v238, 16, v167
	v_and_b32_e32 v239, 0xffff0000, v167
	v_pk_fma_f32 v[122:123], v[58:59], v[236:237], v[122:123]
	v_pk_fma_f32 v[124:125], v[60:61], v[238:239], v[124:125]
	s_nop 0
	v_cvt_pk_bf16_f32 v122, v122, v123
	v_cvt_pk_bf16_f32 v123, v124, v125
	global_store_dwordx2 v169, v[122:123], s[74:75] offset:64
	v_lshlrev_b32_e32 v240, 16, v194
	v_and_b32_e32 v241, 0xffff0000, v194
	v_lshlrev_b32_e32 v242, 16, v195
	v_and_b32_e32 v243, 0xffff0000, v195
	v_pk_fma_f32 v[126:127], v[62:63], v[240:241], v[126:127]
	v_pk_fma_f32 v[128:129], v[64:65], v[242:243], v[128:129]
	s_nop 0
	v_cvt_pk_bf16_f32 v126, v126, v127
	v_cvt_pk_bf16_f32 v127, v128, v129
	global_store_dwordx2 v169, v[126:127], s[74:75] offset:96
	s_add_u32 s78, s78, s79
	s_cmp_gt_u32 s78, 31
	s_cbranch_scc1 .Lbr_exit
	s_barrier
	s_branch .Lbr_tile
.Lbr_exit:
	v_mov_b32_e32 v163, 0
	v_mov_b32_e32 v164, 0x358637bd
	v_mov_b32_e32 v165, 1
	v_mov_b32_e32 v168, 0x2bf
	v_mov_b32_e32 v169, 0
	v_mov_b32_e32 v170, 0x340
	v_mov_b32_e32 v171, 0
	v_mov_b32_e32 v172, 0x33f
	v_mov_b32_e32 v173, 0
	v_mov_b32_e32 v202, 0xc00
	v_mov_b32_e32 v203, 0x7ffffc00
	v_mov_b32_e32 v204, 0xffffff00
	v_mov_b32_e32 v205, 0x400
	v_mov_b32_e32 v206, 0x100
	v_mov_b32_e32 v207, 0x3ff
	v_mov_b32_e32 v208, 0xff
	v_mov_b32_e32 v209, 0xcf
	v_mov_b32_e32 v210, 0xdf
	v_mov_b32_e32 v211, 0xef
	v_mbcnt_lo_u32_b32 v194, -1, 0
	v_mbcnt_hi_u32_b32 v194, -1, v194
	v_and_b32_e32 v195, 64, v194
	v_add_u32_e32 v195, 64, v195
	v_xor_b32_e32 v196, 32, v194
	v_xor_b32_e32 v197, 16, v194
	v_xor_b32_e32 v198, 8, v194
	v_xor_b32_e32 v199, 4, v194
	v_xor_b32_e32 v200, 2, v194
	v_xor_b32_e32 v201, 1, v194
	s_branch .LBB0_309

.LBB0_234:
	s_add_i32 s6, s14, 1
	s_cmp_lg_u32 s14, 2
	s_cselect_b32 s14, s6, 0
	s_cmp_lt_i32 s16, 32
	s_cbranch_scc0 .LBB0_312

.LBB0_245:
	s_and_b32 s7, s17, 3
	s_or_b32 s7, s7, s12
	s_lshl_b32 s6, s17, 5
	s_and_b32 s6, s6, 0xffffff80
	v_readlane_b32 s72, v252, 0
	v_readlane_b32 s73, v252, 1
	v_readlane_b32 s74, v252, 2
	v_readlane_b32 s75, v252, 3
	s_add_i32 s38, s7, -12
	s_lshr_b32 s38, s38, 2
	s_cmp_lt_u32 s7, 16
	s_cselect_b32 s38, 0, s38
	s_cselect_b32 s68, s52, s54
	s_cselect_b32 s69, s53, s55
	s_add_i32 s38, s38, s13
	s_mul_i32 s39, s38, 0x6000
	s_add_u32 s70, s72, s39
	s_addc_u32 s71, s73, 0
	s_add_u32 s70, s70, 0x2000
	s_addc_u32 s71, s71, 0
	s_and_b32 s39, s7, 15
	v_lshl_add_u32 v136, s7, 8, v90
	v_or_b32_e32 v137, s6, v91
	v_lshlrev_b32_e32 v146, 2, v137
	v_lshlrev_b32_e32 v138, 11, v136
	v_lshl_add_u32 v138, v137, 1, v138
	v_add_u32_e32 v139, 0x8000, v138
	v_add_u32_e32 v140, 0x10000, v138
	v_add_u32_e32 v141, 0x18000, v138
	v_lshl_add_u32 v142, s39, 8, v90
	v_lshlrev_b32_e32 v142, 12, v142
	v_add_u32_e32 v142, v142, v146
	v_add_u32_e32 v143, 0x10000, v142
	v_add_u32_e32 v144, 0x20000, v142
	v_add_u32_e32 v145, 0x30000, v142
	global_load_dwordx4 v[120:123], v146, s[70:71] offset:0
	global_load_dwordx4 v[124:127], v146, s[70:71] offset:64
	global_load_dwordx4 v[128:131], v146, s[70:71] offset:128
	global_load_dwordx4 v[132:135], v146, s[70:71] offset:192
	s_and_b64 vcc, exec, s[2:3]
	s_cbranch_vccnz .Lop_ld_bf
	global_load_dwordx4 v[212:215], v142, s[68:69] offset:0
	global_load_dwordx4 v[216:219], v142, s[68:69] offset:64
	global_load_dwordx4 v[220:223], v142, s[68:69] offset:128
	global_load_dwordx4 v[224:227], v142, s[68:69] offset:192
	global_load_dwordx4 v[228:231], v143, s[68:69] offset:0
	global_load_dwordx4 v[232:235], v143, s[68:69] offset:64
	global_load_dwordx4 v[236:239], v143, s[68:69] offset:128
	global_load_dwordx4 v[240:243], v143, s[68:69] offset:192
	global_load_dwordx4 v[244:247], v144, s[68:69] offset:0
	global_load_dwordx4 v[248:251], v144, s[68:69] offset:64
	global_load_dwordx4 v[176:179], v144, s[68:69] offset:128
	global_load_dwordx4 v[180:183], v144, s[68:69] offset:192
	global_load_dwordx4 v[184:187], v145, s[68:69] offset:0
	global_load_dwordx4 v[188:191], v145, s[68:69] offset:64
	global_load_dwordx4 v[112:115], v145, s[68:69] offset:128
	global_load_dwordx4 v[116:119], v145, s[68:69] offset:192
	s_branch .Lop_ld_done
.Lop_ld_bf:
	global_load_dwordx2 v[212:213], v138, s[74:75] offset:0
	global_load_dwordx2 v[216:217], v138, s[74:75] offset:32
	global_load_dwordx2 v[220:221], v138, s[74:75] offset:64
	global_load_dwordx2 v[224:225], v138, s[74:75] offset:96
	global_load_dwordx2 v[228:229], v139, s[74:75] offset:0
	global_load_dwordx2 v[232:233], v139, s[74:75] offset:32
	global_load_dwordx2 v[236:237], v139, s[74:75] offset:64
	global_load_dwordx2 v[240:241], v139, s[74:75] offset:96
	global_load_dwordx2 v[244:245], v140, s[74:75] offset:0
	global_load_dwordx2 v[248:249], v140, s[74:75] offset:32
	global_load_dwordx2 v[176:177], v140, s[74:75] offset:64
	global_load_dwordx2 v[180:181], v140, s[74:75] offset:96
	global_load_dwordx2 v[184:185], v141, s[74:75] offset:0
	global_load_dwordx2 v[188:189], v141, s[74:75] offset:32
	global_load_dwordx2 v[112:113], v141, s[74:75] offset:64
	global_load_dwordx2 v[116:117], v141, s[74:75] offset:96
.Lop_ld_done:
	s_mul_i32 s6, s14, 0xc000
	s_add_i32 s6, s6, 0
	v_add_u32_e32 v82, s6, v86
	v_add_u32_e32 v83, v82, v87
	v_add_u32_e32 v82, v82, v88
	ds_read_b128 v[66:69], v83 offset:32768
	ds_read_b128 v[74:77], v83 offset:34816
	ds_read_b128 v[78:81], v83 offset:36864
	ds_read_b128 v[92:95], v83 offset:38912
	ds_read_b128 v[96:99], v82
	ds_read_b128 v[100:103], v82 offset:2048
	ds_read_b128 v[104:107], v82 offset:4096
	ds_read_b128 v[108:111], v82 offset:6144
	s_waitcnt lgkmcnt(0)
	v_mfma_f32_16x16x32_bf16 v[62:65], v[66:69], v[96:99], v[62:65]
	v_mfma_f32_16x16x32_bf16 v[58:61], v[74:77], v[96:99], v[58:61]
	v_mfma_f32_16x16x32_bf16 v[54:57], v[78:81], v[96:99], v[54:57]
	v_mfma_f32_16x16x32_bf16 v[50:53], v[92:95], v[96:99], v[50:53]
	v_mfma_f32_16x16x32_bf16 v[46:49], v[66:69], v[100:103], v[46:49]
	v_mfma_f32_16x16x32_bf16 v[42:45], v[74:77], v[100:103], v[42:45]
	v_mfma_f32_16x16x32_bf16 v[38:41], v[78:81], v[100:103], v[38:41]
	v_mfma_f32_16x16x32_bf16 v[34:37], v[92:95], v[100:103], v[34:37]
	v_mfma_f32_16x16x32_bf16 v[30:33], v[66:69], v[104:107], v[30:33]
	v_mfma_f32_16x16x32_bf16 v[26:29], v[74:77], v[104:107], v[26:29]
	v_mfma_f32_16x16x32_bf16 v[22:25], v[78:81], v[104:107], v[22:25]
	v_mfma_f32_16x16x32_bf16 v[18:21], v[92:95], v[104:107], v[18:21]
	v_mfma_f32_16x16x32_bf16 v[14:17], v[66:69], v[108:111], v[14:17]
	v_mfma_f32_16x16x32_bf16 v[10:13], v[74:77], v[108:111], v[10:13]
	v_mfma_f32_16x16x32_bf16 v[6:9], v[78:81], v[108:111], v[6:9]
	v_mfma_f32_16x16x32_bf16 v[2:5], v[92:95], v[108:111], v[2:5]
	v_add_u32_e32 v82, s6, v89
	v_add_u32_e32 v83, v82, v87
	v_add_u32_e32 v82, v82, v88
	ds_read_b128 v[66:69], v83 offset:32768
	ds_read_b128 v[74:77], v83 offset:34816
	ds_read_b128 v[78:81], v83 offset:36864
	ds_read_b128 v[92:95], v83 offset:38912
	ds_read_b128 v[96:99], v82
	ds_read_b128 v[100:103], v82 offset:2048
	ds_read_b128 v[104:107], v82 offset:4096
	ds_read_b128 v[108:111], v82 offset:6144
	s_waitcnt lgkmcnt(0)
	v_mfma_f32_16x16x32_bf16 v[62:65], v[66:69], v[96:99], v[62:65]
	v_mfma_f32_16x16x32_bf16 v[58:61], v[74:77], v[96:99], v[58:61]
	v_mfma_f32_16x16x32_bf16 v[54:57], v[78:81], v[96:99], v[54:57]
	v_mfma_f32_16x16x32_bf16 v[50:53], v[92:95], v[96:99], v[50:53]
	v_mfma_f32_16x16x32_bf16 v[46:49], v[66:69], v[100:103], v[46:49]
	v_mfma_f32_16x16x32_bf16 v[42:45], v[74:77], v[100:103], v[42:45]
	v_mfma_f32_16x16x32_bf16 v[38:41], v[78:81], v[100:103], v[38:41]
	v_mfma_f32_16x16x32_bf16 v[34:37], v[92:95], v[100:103], v[34:37]
	v_mfma_f32_16x16x32_bf16 v[30:33], v[66:69], v[104:107], v[30:33]
	v_mfma_f32_16x16x32_bf16 v[26:29], v[74:77], v[104:107], v[26:29]
	v_mfma_f32_16x16x32_bf16 v[22:25], v[78:81], v[104:107], v[22:25]
	v_mfma_f32_16x16x32_bf16 v[18:21], v[92:95], v[104:107], v[18:21]
	v_mfma_f32_16x16x32_bf16 v[14:17], v[66:69], v[108:111], v[14:17]
	v_mfma_f32_16x16x32_bf16 v[10:13], v[74:77], v[108:111], v[10:13]
	v_mfma_f32_16x16x32_bf16 v[6:9], v[78:81], v[108:111], v[6:9]
	v_mfma_f32_16x16x32_bf16 v[2:5], v[92:95], v[108:111], v[2:5]
	s_nop 4
	s_and_b64 vcc, exec, s[2:3]
	s_cbranch_vccnz .Lop_cv_bf
	s_waitcnt vmcnt(15)
	v_pk_fma_f32 v[64:65], v[64:65], v[122:123], v[214:215]
	v_pk_fma_f32 v[62:63], v[62:63], v[120:121], v[212:213]
	s_nop 0
	v_cvt_pk_bf16_f32 v62, v62, v63
	v_cvt_pk_bf16_f32 v63, v64, v65
	global_store_dwordx2 v138, v[62:63], s[74:75] offset:0
	s_waitcnt vmcnt(15)
	v_pk_fma_f32 v[60:61], v[60:61], v[126:127], v[218:219]
	v_pk_fma_f32 v[58:59], v[58:59], v[124:125], v[216:217]
	s_nop 0
	v_cvt_pk_bf16_f32 v58, v58, v59
	v_cvt_pk_bf16_f32 v59, v60, v61
	global_store_dwordx2 v138, v[58:59], s[74:75] offset:32
	s_waitcnt vmcnt(15)
	v_pk_fma_f32 v[56:57], v[56:57], v[130:131], v[222:223]
	v_pk_fma_f32 v[54:55], v[54:55], v[128:129], v[220:221]
	s_nop 0
	v_cvt_pk_bf16_f32 v54, v54, v55
	v_cvt_pk_bf16_f32 v55, v56, v57
	global_store_dwordx2 v138, v[54:55], s[74:75] offset:64
	s_waitcnt vmcnt(15)
	v_pk_fma_f32 v[52:53], v[52:53], v[134:135], v[226:227]
	v_pk_fma_f32 v[50:51], v[50:51], v[132:133], v[224:225]
	s_nop 0
	v_cvt_pk_bf16_f32 v50, v50, v51
	v_cvt_pk_bf16_f32 v51, v52, v53
	global_store_dwordx2 v138, v[50:51], s[74:75] offset:96
	s_waitcnt vmcnt(15)
	v_pk_fma_f32 v[48:49], v[48:49], v[122:123], v[230:231]
	v_pk_fma_f32 v[46:47], v[46:47], v[120:121], v[228:229]
	s_nop 0
	v_cvt_pk_bf16_f32 v46, v46, v47
	v_cvt_pk_bf16_f32 v47, v48, v49
	global_store_dwordx2 v139, v[46:47], s[74:75] offset:0
	s_waitcnt vmcnt(15)
	v_pk_fma_f32 v[44:45], v[44:45], v[126:127], v[234:235]
	v_pk_fma_f32 v[42:43], v[42:43], v[124:125], v[232:233]
	s_nop 0
	v_cvt_pk_bf16_f32 v42, v42, v43
	v_cvt_pk_bf16_f32 v43, v44, v45
	global_store_dwordx2 v139, v[42:43], s[74:75] offset:32
	s_waitcnt vmcnt(15)
	v_pk_fma_f32 v[40:41], v[40:41], v[130:131], v[238:239]
	v_pk_fma_f32 v[38:39], v[38:39], v[128:129], v[236:237]
	s_nop 0
	v_cvt_pk_bf16_f32 v38, v38, v39
	v_cvt_pk_bf16_f32 v39, v40, v41
	global_store_dwordx2 v139, v[38:39], s[74:75] offset:64
	s_waitcnt vmcnt(15)
	v_pk_fma_f32 v[36:37], v[36:37], v[134:135], v[242:243]
	v_pk_fma_f32 v[34:35], v[34:35], v[132:133], v[240:241]
	s_nop 0
	v_cvt_pk_bf16_f32 v34, v34, v35
	v_cvt_pk_bf16_f32 v35, v36, v37
	global_store_dwordx2 v139, v[34:35], s[74:75] offset:96
	s_waitcnt vmcnt(15)
	v_pk_fma_f32 v[32:33], v[32:33], v[122:123], v[246:247]
	v_pk_fma_f32 v[30:31], v[30:31], v[120:121], v[244:245]
	s_nop 0
	v_cvt_pk_bf16_f32 v30, v30, v31
	v_cvt_pk_bf16_f32 v31, v32, v33
	global_store_dwordx2 v140, v[30:31], s[74:75] offset:0
	s_waitcnt vmcnt(15)
	v_pk_fma_f32 v[28:29], v[28:29], v[126:127], v[250:251]
	v_pk_fma_f32 v[26:27], v[26:27], v[124:125], v[248:249]
	s_nop 0
	v_cvt_pk_bf16_f32 v26, v26, v27
	v_cvt_pk_bf16_f32 v27, v28, v29
	global_store_dwordx2 v140, v[26:27], s[74:75] offset:32
	s_waitcnt vmcnt(15)
	v_pk_fma_f32 v[24:25], v[24:25], v[130:131], v[178:179]
	v_pk_fma_f32 v[22:23], v[22:23], v[128:129], v[176:177]
	s_nop 0
	v_cvt_pk_bf16_f32 v22, v22, v23
	v_cvt_pk_bf16_f32 v23, v24, v25
	global_store_dwordx2 v140, v[22:23], s[74:75] offset:64
	s_waitcnt vmcnt(15)
	v_pk_fma_f32 v[20:21], v[20:21], v[134:135], v[182:183]
	v_pk_fma_f32 v[18:19], v[18:19], v[132:133], v[180:181]
	s_nop 0
	v_cvt_pk_bf16_f32 v18, v18, v19
	v_cvt_pk_bf16_f32 v19, v20, v21
	global_store_dwordx2 v140, v[18:19], s[74:75] offset:96
	s_waitcnt vmcnt(15)
	v_pk_fma_f32 v[16:17], v[16:17], v[122:123], v[186:187]
	v_pk_fma_f32 v[14:15], v[14:15], v[120:121], v[184:185]
	s_nop 0
	v_cvt_pk_bf16_f32 v14, v14, v15
	v_cvt_pk_bf16_f32 v15, v16, v17
	global_store_dwordx2 v141, v[14:15], s[74:75] offset:0
	s_waitcnt vmcnt(15)
	v_pk_fma_f32 v[12:13], v[12:13], v[126:127], v[190:191]
	v_pk_fma_f32 v[10:11], v[10:11], v[124:125], v[188:189]
	s_nop 0
	v_cvt_pk_bf16_f32 v10, v10, v11
	v_cvt_pk_bf16_f32 v11, v12, v13
	global_store_dwordx2 v141, v[10:11], s[74:75] offset:32
	s_waitcnt vmcnt(15)
	v_pk_fma_f32 v[8:9], v[8:9], v[130:131], v[114:115]
	v_pk_fma_f32 v[6:7], v[6:7], v[128:129], v[112:113]
	s_nop 0
	v_cvt_pk_bf16_f32 v6, v6, v7
	v_cvt_pk_bf16_f32 v7, v8, v9
	global_store_dwordx2 v141, v[6:7], s[74:75] offset:64
	s_waitcnt vmcnt(15)
	v_pk_fma_f32 v[4:5], v[4:5], v[134:135], v[118:119]
	v_pk_fma_f32 v[2:3], v[2:3], v[132:133], v[116:117]
	s_nop 0
	v_cvt_pk_bf16_f32 v2, v2, v3
	v_cvt_pk_bf16_f32 v3, v4, v5
	global_store_dwordx2 v141, v[2:3], s[74:75] offset:96
	s_branch .LBB0_234
.Lop_cv_bf:
	s_waitcnt vmcnt(15)
	v_lshlrev_b32_e32 v214, 16, v213
	v_and_b32_e32 v215, 0xffff0000, v213
	v_and_b32_e32 v213, 0xffff0000, v212
	v_lshlrev_b32_e32 v212, 16, v212
	v_pk_fma_f32 v[64:65], v[64:65], v[122:123], v[214:215]
	v_pk_fma_f32 v[62:63], v[62:63], v[120:121], v[212:213]
	s_nop 0
	v_cvt_pk_bf16_f32 v62, v62, v63
	v_cvt_pk_bf16_f32 v63, v64, v65
	global_store_dwordx2 v138, v[62:63], s[74:75] offset:0
	s_waitcnt vmcnt(15)
	v_lshlrev_b32_e32 v218, 16, v217
	v_and_b32_e32 v219, 0xffff0000, v217
	v_and_b32_e32 v217, 0xffff0000, v216
	v_lshlrev_b32_e32 v216, 16, v216
	v_pk_fma_f32 v[60:61], v[60:61], v[126:127], v[218:219]
	v_pk_fma_f32 v[58:59], v[58:59], v[124:125], v[216:217]
	s_nop 0
	v_cvt_pk_bf16_f32 v58, v58, v59
	v_cvt_pk_bf16_f32 v59, v60, v61
	global_store_dwordx2 v138, v[58:59], s[74:75] offset:32
	s_waitcnt vmcnt(15)
	v_lshlrev_b32_e32 v222, 16, v221
	v_and_b32_e32 v223, 0xffff0000, v221
	v_and_b32_e32 v221, 0xffff0000, v220
	v_lshlrev_b32_e32 v220, 16, v220
	v_pk_fma_f32 v[56:57], v[56:57], v[130:131], v[222:223]
	v_pk_fma_f32 v[54:55], v[54:55], v[128:129], v[220:221]
	s_nop 0
	v_cvt_pk_bf16_f32 v54, v54, v55
	v_cvt_pk_bf16_f32 v55, v56, v57
	global_store_dwordx2 v138, v[54:55], s[74:75] offset:64
	s_waitcnt vmcnt(15)
	v_lshlrev_b32_e32 v226, 16, v225
	v_and_b32_e32 v227, 0xffff0000, v225
	v_and_b32_e32 v225, 0xffff0000, v224
	v_lshlrev_b32_e32 v224, 16, v224
	v_pk_fma_f32 v[52:53], v[52:53], v[134:135], v[226:227]
	v_pk_fma_f32 v[50:51], v[50:51], v[132:133], v[224:225]
	s_nop 0
	v_cvt_pk_bf16_f32 v50, v50, v51
	v_cvt_pk_bf16_f32 v51, v52, v53
	global_store_dwordx2 v138, v[50:51], s[74:75] offset:96
	s_waitcnt vmcnt(15)
	v_lshlrev_b32_e32 v230, 16, v229
	v_and_b32_e32 v231, 0xffff0000, v229
	v_and_b32_e32 v229, 0xffff0000, v228
	v_lshlrev_b32_e32 v228, 16, v228
	v_pk_fma_f32 v[48:49], v[48:49], v[122:123], v[230:231]
	v_pk_fma_f32 v[46:47], v[46:47], v[120:121], v[228:229]
	s_nop 0
	v_cvt_pk_bf16_f32 v46, v46, v47
	v_cvt_pk_bf16_f32 v47, v48, v49
	global_store_dwordx2 v139, v[46:47], s[74:75] offset:0
	s_waitcnt vmcnt(15)
	v_lshlrev_b32_e32 v234, 16, v233
	v_and_b32_e32 v235, 0xffff0000, v233
	v_and_b32_e32 v233, 0xffff0000, v232
	v_lshlrev_b32_e32 v232, 16, v232
	v_pk_fma_f32 v[44:45], v[44:45], v[126:127], v[234:235]
	v_pk_fma_f32 v[42:43], v[42:43], v[124:125], v[232:233]
	s_nop 0
	v_cvt_pk_bf16_f32 v42, v42, v43
	v_cvt_pk_bf16_f32 v43, v44, v45
	global_store_dwordx2 v139, v[42:43], s[74:75] offset:32
	s_waitcnt vmcnt(15)
	v_lshlrev_b32_e32 v238, 16, v237
	v_and_b32_e32 v239, 0xffff0000, v237
	v_and_b32_e32 v237, 0xffff0000, v236
	v_lshlrev_b32_e32 v236, 16, v236
	v_pk_fma_f32 v[40:41], v[40:41], v[130:131], v[238:239]
	v_pk_fma_f32 v[38:39], v[38:39], v[128:129], v[236:237]
	s_nop 0
	v_cvt_pk_bf16_f32 v38, v38, v39
	v_cvt_pk_bf16_f32 v39, v40, v41
	global_store_dwordx2 v139, v[38:39], s[74:75] offset:64
	s_waitcnt vmcnt(15)
	v_lshlrev_b32_e32 v242, 16, v241
	v_and_b32_e32 v243, 0xffff0000, v241
	v_and_b32_e32 v241, 0xffff0000, v240
	v_lshlrev_b32_e32 v240, 16, v240
	v_pk_fma_f32 v[36:37], v[36:37], v[134:135], v[242:243]
	v_pk_fma_f32 v[34:35], v[34:35], v[132:133], v[240:241]
	s_nop 0
	v_cvt_pk_bf16_f32 v34, v34, v35
	v_cvt_pk_bf16_f32 v35, v36, v37
	global_store_dwordx2 v139, v[34:35], s[74:75] offset:96
	s_waitcnt vmcnt(15)
	v_lshlrev_b32_e32 v246, 16, v245
	v_and_b32_e32 v247, 0xffff0000, v245
	v_and_b32_e32 v245, 0xffff0000, v244
	v_lshlrev_b32_e32 v244, 16, v244
	v_pk_fma_f32 v[32:33], v[32:33], v[122:123], v[246:247]
	v_pk_fma_f32 v[30:31], v[30:31], v[120:121], v[244:245]
	s_nop 0
	v_cvt_pk_bf16_f32 v30, v30, v31
	v_cvt_pk_bf16_f32 v31, v32, v33
	global_store_dwordx2 v140, v[30:31], s[74:75] offset:0
	s_waitcnt vmcnt(15)
	v_lshlrev_b32_e32 v250, 16, v249
	v_and_b32_e32 v251, 0xffff0000, v249
	v_and_b32_e32 v249, 0xffff0000, v248
	v_lshlrev_b32_e32 v248, 16, v248
	v_pk_fma_f32 v[28:29], v[28:29], v[126:127], v[250:251]
	v_pk_fma_f32 v[26:27], v[26:27], v[124:125], v[248:249]
	s_nop 0
	v_cvt_pk_bf16_f32 v26, v26, v27
	v_cvt_pk_bf16_f32 v27, v28, v29
	global_store_dwordx2 v140, v[26:27], s[74:75] offset:32
	s_waitcnt vmcnt(15)
	v_lshlrev_b32_e32 v178, 16, v177
	v_and_b32_e32 v179, 0xffff0000, v177
	v_and_b32_e32 v177, 0xffff0000, v176
	v_lshlrev_b32_e32 v176, 16, v176
	v_pk_fma_f32 v[24:25], v[24:25], v[130:131], v[178:179]
	v_pk_fma_f32 v[22:23], v[22:23], v[128:129], v[176:177]
	s_nop 0
	v_cvt_pk_bf16_f32 v22, v22, v23
	v_cvt_pk_bf16_f32 v23, v24, v25
	global_store_dwordx2 v140, v[22:23], s[74:75] offset:64
	s_waitcnt vmcnt(15)
	v_lshlrev_b32_e32 v182, 16, v181
	v_and_b32_e32 v183, 0xffff0000, v181
	v_and_b32_e32 v181, 0xffff0000, v180
	v_lshlrev_b32_e32 v180, 16, v180
	v_pk_fma_f32 v[20:21], v[20:21], v[134:135], v[182:183]
	v_pk_fma_f32 v[18:19], v[18:19], v[132:133], v[180:181]
	s_nop 0
	v_cvt_pk_bf16_f32 v18, v18, v19
	v_cvt_pk_bf16_f32 v19, v20, v21
	global_store_dwordx2 v140, v[18:19], s[74:75] offset:96
	s_waitcnt vmcnt(15)
	v_lshlrev_b32_e32 v186, 16, v185
	v_and_b32_e32 v187, 0xffff0000, v185
	v_and_b32_e32 v185, 0xffff0000, v184
	v_lshlrev_b32_e32 v184, 16, v184
	v_pk_fma_f32 v[16:17], v[16:17], v[122:123], v[186:187]
	v_pk_fma_f32 v[14:15], v[14:15], v[120:121], v[184:185]
	s_nop 0
	v_cvt_pk_bf16_f32 v14, v14, v15
	v_cvt_pk_bf16_f32 v15, v16, v17
	global_store_dwordx2 v141, v[14:15], s[74:75] offset:0
	s_waitcnt vmcnt(15)
	v_lshlrev_b32_e32 v190, 16, v189
	v_and_b32_e32 v191, 0xffff0000, v189
	v_and_b32_e32 v189, 0xffff0000, v188
	v_lshlrev_b32_e32 v188, 16, v188
	v_pk_fma_f32 v[12:13], v[12:13], v[126:127], v[190:191]
	v_pk_fma_f32 v[10:11], v[10:11], v[124:125], v[188:189]
	s_nop 0
	v_cvt_pk_bf16_f32 v10, v10, v11
	v_cvt_pk_bf16_f32 v11, v12, v13
	global_store_dwordx2 v141, v[10:11], s[74:75] offset:32
	s_waitcnt vmcnt(15)
	v_lshlrev_b32_e32 v114, 16, v113
	v_and_b32_e32 v115, 0xffff0000, v113
	v_and_b32_e32 v113, 0xffff0000, v112
	v_lshlrev_b32_e32 v112, 16, v112
	v_pk_fma_f32 v[8:9], v[8:9], v[130:131], v[114:115]
	v_pk_fma_f32 v[6:7], v[6:7], v[128:129], v[112:113]
	s_nop 0
	v_cvt_pk_bf16_f32 v6, v6, v7
	v_cvt_pk_bf16_f32 v7, v8, v9
	global_store_dwordx2 v141, v[6:7], s[74:75] offset:64
	s_waitcnt vmcnt(15)
	v_lshlrev_b32_e32 v118, 16, v117
	v_and_b32_e32 v119, 0xffff0000, v117
	v_and_b32_e32 v117, 0xffff0000, v116
	v_lshlrev_b32_e32 v116, 16, v116
	v_pk_fma_f32 v[4:5], v[4:5], v[134:135], v[118:119]
	v_pk_fma_f32 v[2:3], v[2:3], v[132:133], v[116:117]
	s_nop 0
	v_cvt_pk_bf16_f32 v2, v2, v3
	v_cvt_pk_bf16_f32 v3, v4, v5
	global_store_dwordx2 v141, v[2:3], s[74:75] offset:96
	s_branch .LBB0_234
